# EpiResid (out-proj, FFN2/3 down): next row-group's residual loads issued before the current group's stores (staged in free VGPRs); attention bias-table loads batched
# baseline (speedup 1.0000x reference)
; __device__ __forceinline__ void attn_unit(int u, const bf16_t* QB, const bf16_t* KB, const bf16_t* VTL, const bf16_t* VTC, const float* rpb, bf16_t* MIX, LAS float* rl, int lane) {
;     ...
;     for (int i = lane; i < 465; i += 64) { const int ro = i / 31, co = i - ro * 31; rl[ro * 32 + co] = rpb[h * 465 + i]; }
;     asm volatile("s_waitcnt lgkmcnt(0)" ::: "memory");
.LBB0_682:
	v_bfe_u32 v2, v181, 6, 3
	v_mul_u32_u24_e32 v0, 0x1d1, v2
	v_readlane_b32 s52, v253, 0
	v_add_lshl_u32 v0, v178, v0, 2
	v_readlane_b32 s64, v253, 12
	v_readlane_b32 s65, v253, 13
	v_readlane_b32 s53, v253, 1
	v_readlane_b32 s54, v253, 2
	v_readlane_b32 s55, v253, 3
	v_readlane_b32 s56, v253, 4
	v_readlane_b32 s57, v253, 5
	global_load_dword v3, v0, s[64:65]
	v_readlane_b32 s58, v253, 6
	v_readlane_b32 s59, v253, 7
	v_readlane_b32 s60, v253, 8
	v_readlane_b32 s61, v253, 9
	v_readlane_b32 s62, v253, 10
	v_readlane_b32 s63, v253, 11
	v_readlane_b32 s66, v253, 14
	v_readlane_b32 s67, v253, 15
	global_load_dword v231, v0, s[64:65] offset:256
	global_load_dword v232, v0, s[64:65] offset:512
	global_load_dword v233, v0, s[64:65] offset:768
	global_load_dword v234, v0, s[64:65] offset:1024
	global_load_dword v235, v0, s[64:65] offset:1280
	global_load_dword v236, v0, s[64:65] offset:1536
	s_waitcnt vmcnt(0)
	ds_write_b32 v165, v3 offset:40960
	ds_write_b32 v179, v231 offset:41216
	ds_write_b32 v188, v232 offset:41472
	ds_write_b32 v189, v233 offset:41728
	ds_write_b32 v190, v234 offset:41984
	ds_write_b32 v191, v235 offset:42240
	ds_write_b32 v192, v236 offset:42496
	s_mov_b64 s[44:45], exec
	v_readlane_b32 s50, v252, 29
	v_readlane_b32 s51, v252, 30
	s_and_b64 s[50:51], s[44:45], s[50:51]
	s_mov_b64 exec, s[50:51]
	s_cbranch_execz .LBB0_684
	v_readlane_b32 s52, v253, 0
	v_readlane_b32 s64, v253, 12
	v_readlane_b32 s65, v253, 13
	v_readlane_b32 s53, v253, 1
	v_readlane_b32 s54, v253, 2
	v_lshl_add_u64 v[4:5], s[64:65], 0, v[0:1]
	global_load_dword v0, v[4:5], off offset:1792
	v_readlane_b32 s55, v253, 3
	v_readlane_b32 s56, v253, 4
	v_readlane_b32 s57, v253, 5
	v_readlane_b32 s58, v253, 6
	v_readlane_b32 s59, v253, 7
	v_readlane_b32 s60, v253, 8
	v_readlane_b32 s61, v253, 9
	v_readlane_b32 s62, v253, 10
	v_readlane_b32 s63, v253, 11
	v_readlane_b32 s66, v253, 14
	v_readlane_b32 s67, v253, 15
	s_waitcnt vmcnt(0)
	ds_write_b32 v193, v0 offset:42752

;     __device__ __forceinline__ void operator()(const f32x4 (&acc)[2][2][4][2], const Unit& u, int wr, int wc, int fr, int fq) const {
;         const int row0 = u.pm * 256 + wr * 64 + fr, col0 = u.pn * 256 + wc * 32 + 8 * fq;
;         const int mb = u.pm < 64 ? (u.pm >> 4) : 4;
;         float* SSn = (float*)(ws + WS_SS) + ss_off;
;         const float* gate = (const float*)(ws + WS_MOD) + gate_off + (size_t)mb * 9216; const float* gn = (const float*)(ws + WS_NG) + gn_off; const float* scn = (const float*)(ws + WS_MOD) + scn_off + (size_t)mb * 9216;
;         f32x4 gv[2][2], bv[2][2], wv[2][2];
; #pragma unroll
;         for (int bj = 0; bj < 2; ++bj)
; #pragma unroll
;             for (int n = 0; n < 2; ++n) { const int cc = col0 + bj * 128 + 4 * n;
;                 gv[bj][n] = *(const f32x4*)(gate + cc) * gmul;
;                 bv[bj][n] = HASBIAS ? *(const f32x4*)(bias + cc) : (f32x4){0.f, 0.f, 0.f, 0.f};
;                 wv[bj][n] = FUSE ? *(const f32x4*)(gn + cc) * (*(const f32x4*)(scn + cc) + 1.0f) : (f32x4){0.f, 0.f, 0.f, 0.f}; }
;         const unsigned e0 = (unsigned)(row0 * D + col0);
;         const char* bsc = (const char*)base0; char* Hc = (char*)(ws + WS_H); char* HBc = (char*)(ws + WS_XN);
;         constexpr int RGB = 2;
; #pragma unroll
;         for (int rg = 0; rg < 8 / RGB; ++rg) {
;             u32x4 braw[INPLACE ? RGB : 1][2]; f32x4 bb[INPLACE ? 1 : RGB][2][2];
; #pragma unroll
;             for (int mm = 0; mm < RGB; ++mm) { const int q = rg * RGB + mm, ai = q >> 2, m = q & 3;
; #pragma unroll
;                 for (int bj = 0; bj < 2; ++bj) { const unsigned e = e0 + (unsigned)((ai * 128 + m * 16) * D + bj * 128);
;                     if constexpr (INPLACE) braw[mm][bj] = *(const u32x4*)(Hc + (size_t)(e * 2u));
;                     else { bb[mm][bj][0] = *(const f32x4*)(bsc + (size_t)(e * 4u)); bb[mm][bj][1] = *(const f32x4*)(bsc + (size_t)(e * 4u + 16u)); } } }
; #pragma unroll
;             for (int mm = 0; mm < RGB; ++mm) { const int q = rg * RGB + mm, ai = q >> 2, m = q & 3; float ssum = 0.f;
; #pragma unroll
;                 for (int bj = 0; bj < 2; ++bj) { const unsigned e = e0 + (unsigned)((ai * 128 + m * 16) * D + bj * 128);
;                     f32x4 r0, r1;
;                     if constexpr (INPLACE) { const u32x4 q4 = braw[mm][bj];
.LBB0_888:
	v_lshl_add_u32 v56, s24, 8, v179
	s_ashr_i32 s19, s24, 4
	v_lshl_or_b32 v0, s51, 8, v192
	s_mul_hi_i32 s26, s19, 0x9000
	s_waitcnt lgkmcnt(0)
	v_lshlrev_b32_e32 v1, 11, v56
	s_mul_i32 s19, s19, 0x9000
	v_lshl_add_u32 v196, v0, 1, v1
	s_add_u32 s24, s45, s19
	v_ashrrev_i32_e32 v1, 31, v0
	s_addc_u32 s25, s46, s26
	v_lshlrev_b64 v[2:3], 2, v[0:1]
	v_or_b32_e32 v57, 0x100, v196
	v_lshl_add_u64 v[16:17], s[24:25], 0, v[2:3]
	s_add_u32 s24, s47, s19
	global_load_dwordx4 v[198:201], v57, s[14:15]
	global_load_dwordx4 v[74:77], v196, s[14:15]
	s_addc_u32 s25, s48, s26
	global_load_dwordx4 v[12:15], v[16:17], off
	global_load_dwordx4 v[8:11], v[16:17], off offset:16
	v_lshl_add_u64 v[4:5], s[24:25], 0, v[2:3]
	v_lshl_add_u64 v[2:3], s[10:11], 0, v[2:3]
	global_load_dwordx4 v[80:83], v[4:5], off
	global_load_dwordx4 v[98:101], v[4:5], off offset:16
	global_load_dwordx4 v[102:105], v[4:5], off offset:512
	global_load_dwordx4 v[202:205], v[4:5], off offset:528
	global_load_dwordx4 v[206:209], v[2:3], off offset:16
	global_load_dwordx4 v[210:213], v[2:3], off
	v_or_b32_e32 v0, 0x80, v0
	v_ashrrev_i32_e32 v1, 31, v0
	v_lshl_add_u64 v[0:1], v[0:1], 2, s[10:11]
	global_load_dwordx4 v[214:217], v[0:1], off
	global_load_dwordx4 v[218:221], v[0:1], off offset:16
	global_load_dwordx4 v[4:7], v[16:17], off offset:512
	s_nop 0
	global_load_dwordx4 v[0:3], v[16:17], off offset:528
	v_add_u32_e32 v136, 0x8000, v196
	v_add_u32_e32 v190, 0x8100, v196
	global_load_dwordx4 v[20:23], v136, s[14:15]
	global_load_dwordx4 v[16:19], v190, s[14:15]
	s_waitcnt vmcnt(0)
	v_add_u32_e32 v252, 0x10000, v196
	global_load_dwordx4 v[238:241], v252, s[14:15]
	global_load_dwordx4 v[242:245], v252, s[14:15] offset:256
	v_add_u32_e32 v252, 0x18000, v196
	global_load_dwordx4 v[246:249], v252, s[14:15]
	global_load_dwordx2 v[250:251], v252, s[14:15] offset:256
	global_load_dwordx2 v[254:255], v252, s[14:15] offset:264
	v_lshlrev_b32_e32 v222, 16, v198
	v_lshlrev_b32_e32 v224, 16, v74
	v_and_b32_e32 v225, 0xffff0000, v74
	v_lshlrev_b32_e32 v74, 16, v75
	v_and_b32_e32 v75, 0xffff0000, v75
	v_lshlrev_b32_e32 v226, 16, v76
	v_and_b32_e32 v227, 0xffff0000, v76
	v_lshlrev_b32_e32 v76, 16, v77
	v_and_b32_e32 v77, 0xffff0000, v77
	v_pk_fma_f32 v[228:229], v[182:183], v[14:15], v[74:75]
	v_pk_fma_f32 v[186:187], v[186:187], v[10:11], v[76:77]
	v_pk_add_f32 v[74:75], v[82:83], 1.0 op_sel_hi:[1,0]
	v_pk_add_f32 v[76:77], v[80:81], 1.0 op_sel_hi:[1,0]
	v_pk_fma_f32 v[224:225], v[184:185], v[12:13], v[224:225]
	v_pk_fma_f32 v[188:189], v[188:189], v[8:9], v[226:227]
	v_pk_add_f32 v[80:81], v[100:101], 1.0 op_sel_hi:[1,0]
	v_pk_add_f32 v[82:83], v[98:99], 1.0 op_sel_hi:[1,0]
	v_pk_add_f32 v[226:227], v[104:105], 1.0 op_sel_hi:[1,0]
	v_pk_add_f32 v[230:231], v[102:103], 1.0 op_sel_hi:[1,0]
	v_cvt_pk_bf16_f32 v182, v224, v225
	v_cvt_pk_bf16_f32 v183, v228, v229
	v_cvt_pk_bf16_f32 v184, v188, v189
	v_cvt_pk_bf16_f32 v185, v186, v187
	v_pk_mul_f32 v[102:103], v[212:213], v[74:75]
	v_pk_mul_f32 v[104:105], v[210:211], v[76:77]
	v_mul_f32_e32 v191, v225, v225
	v_mul_f32_e32 v197, v229, v229
	v_mul_f32_e32 v223, v189, v189
	v_mul_f32_e32 v232, v187, v187
	v_pk_mul_f32 v[98:99], v[208:209], v[80:81]
	v_pk_mul_f32 v[100:101], v[206:207], v[82:83]
	global_store_dwordx4 v196, v[182:185], s[14:15]
	v_fmac_f32_e32 v191, v224, v224
	v_fmac_f32_e32 v197, v228, v228
	v_pk_mul_f32 v[184:185], v[102:103], v[228:229]
	v_pk_mul_f32 v[182:183], v[104:105], v[224:225]
	v_fmac_f32_e32 v223, v188, v188
	v_fmac_f32_e32 v232, v186, v186
	v_pk_mul_f32 v[186:187], v[98:99], v[186:187]
	v_pk_mul_f32 v[188:189], v[100:101], v[188:189]
	v_cvt_pk_bf16_f32 v182, v182, v183
	v_cvt_pk_bf16_f32 v183, v184, v185
	v_add_f32_e32 v191, v191, v197
	v_cvt_pk_bf16_f32 v184, v188, v189
	v_cvt_pk_bf16_f32 v185, v186, v187
	v_add_f32_e32 v197, v223, v232
	global_store_dwordx4 v196, v[182:185], s[86:87]
	v_and_b32_e32 v223, 0xffff0000, v198
	v_lshlrev_b32_e32 v186, 16, v201
	v_lshlrev_b32_e32 v182, 16, v199
	v_and_b32_e32 v183, 0xffff0000, v199
	v_lshlrev_b32_e32 v184, 16, v200
	v_and_b32_e32 v185, 0xffff0000, v200
	v_and_b32_e32 v187, 0xffff0000, v201
	v_pk_fma_f32 v[174:175], v[174:175], v[6:7], v[182:183]
	v_pk_fma_f32 v[172:173], v[172:173], v[4:5], v[222:223]
	v_pk_fma_f32 v[184:185], v[168:169], v[0:1], v[184:185]
	v_cvt_pk_bf16_f32 v168, v172, v173
	v_cvt_pk_bf16_f32 v169, v174, v175
	v_pk_fma_f32 v[182:183], v[170:171], v[2:3], v[186:187]
	v_cvt_pk_bf16_f32 v170, v184, v185
	v_add_f32_e32 v191, v191, v197
	v_cvt_pk_bf16_f32 v171, v182, v183
	global_store_dwordx4 v57, v[168:171], s[14:15]
	v_pk_mul_f32 v[82:83], v[214:215], v[230:231]
	v_pk_add_f32 v[204:205], v[204:205], 1.0 op_sel_hi:[1,0]
	v_mul_f32_e32 v168, v173, v173
	v_mul_f32_e32 v169, v175, v175
	v_fmac_f32_e32 v168, v172, v172
	v_fmac_f32_e32 v169, v174, v174
	v_add_f32_e32 v168, v168, v169
	v_mul_f32_e32 v169, v185, v185
	v_mul_f32_e32 v170, v183, v183
	v_fmac_f32_e32 v169, v184, v184
	v_fmac_f32_e32 v170, v182, v182
	v_add_f32_e32 v169, v169, v170
	v_add_f32_e32 v168, v168, v169
	v_and_b32_e32 v170, 64, v177
	v_add_f32_e32 v169, v191, v168
	v_xor_b32_e32 v168, 16, v177
	v_add_u32_e32 v186, 64, v170
	v_cmp_lt_i32_e32 vcc, v168, v186
	v_pk_mul_f32 v[170:171], v[82:83], v[172:173]
	v_pk_add_f32 v[202:203], v[202:203], 1.0 op_sel_hi:[1,0]
	v_cndmask_b32_e32 v168, v177, v168, vcc
	v_lshlrev_b32_e32 v168, 2, v168
	ds_bpermute_b32 v187, v168, v169
	v_cvt_pk_bf16_f32 v172, v170, v171
	v_pk_mul_f32 v[80:81], v[216:217], v[226:227]
	v_pk_mul_f32 v[74:75], v[220:221], v[204:205]
	v_pk_mul_f32 v[76:77], v[218:219], v[202:203]
	s_waitcnt lgkmcnt(0)
	v_add_f32_e32 v170, v169, v187
	v_xor_b32_e32 v169, 32, v177
	v_cmp_lt_i32_e32 vcc, v169, v186
	v_pk_mul_f32 v[174:175], v[80:81], v[174:175]
	v_pk_mul_f32 v[182:183], v[74:75], v[182:183]
	v_cndmask_b32_e32 v169, v177, v169, vcc
	v_lshlrev_b32_e32 v169, 2, v169
	ds_bpermute_b32 v171, v169, v170
	v_pk_mul_f32 v[184:185], v[76:77], v[184:185]
	v_cvt_pk_bf16_f32 v173, v174, v175
	s_nop 0
	v_cvt_pk_bf16_f32 v174, v184, v185
	v_cvt_pk_bf16_f32 v175, v182, v183
	global_store_dwordx4 v57, v[172:175], s[86:87]
	s_and_saveexec_b64 s[24:25], s[0:1]
	s_cbranch_execz .LBB0_890
	v_mov_b32_e32 v57, v137
	v_lshl_add_u64 v[172:173], v[56:57], 2, s[12:13]
	s_waitcnt lgkmcnt(0)
	v_add_f32_e32 v57, v170, v171
	global_atomic_add_f32 v[172:173], v57, off

;     __device__ __forceinline__ void operator()(const f32x4 (&acc)[2][2][4][2], const Unit& u, int wr, int wc, int fr, int fq) const {
;     ...
;         for (int rg = 0; rg < 8 / RGB; ++rg) {
;             u32x4 braw[INPLACE ? RGB : 1][2]; f32x4 bb[INPLACE ? 1 : RGB][2][2];
; #pragma unroll
;             for (int mm = 0; mm < RGB; ++mm) { const int q = rg * RGB + mm, ai = q >> 2, m = q & 3;
; #pragma unroll
;                 for (int bj = 0; bj < 2; ++bj) { const unsigned e = e0 + (unsigned)((ai * 128 + m * 16) * D + bj * 128);
;                     if constexpr (INPLACE) braw[mm][bj] = *(const u32x4*)(Hc + (size_t)(e * 2u));
;                     else { bb[mm][bj][0] = *(const f32x4*)(bsc + (size_t)(e * 4u)); bb[mm][bj][1] = *(const f32x4*)(bsc + (size_t)(e * 4u + 16u)); } } }
; #pragma unroll
;             for (int mm = 0; mm < RGB; ++mm) { const int q = rg * RGB + mm, ai = q >> 2, m = q & 3; float ssum = 0.f;
; #pragma unroll
;                 for (int bj = 0; bj < 2; ++bj) { const unsigned e = e0 + (unsigned)((ai * 128 + m * 16) * D + bj * 128);
;                     f32x4 r0, r1;
;                     if constexpr (INPLACE) { const u32x4 q4 = braw[mm][bj];
;                         r0 = (f32x4){__uint_as_float(q4[0] << 16), __uint_as_float(q4[0] & 0xffff0000u), __uint_as_float(q4[1] << 16), __uint_as_float(q4[1] & 0xffff0000u)};
;                         r1 = (f32x4){__uint_as_float(q4[2] << 16), __uint_as_float(q4[2] & 0xffff0000u), __uint_as_float(q4[3] << 16), __uint_as_float(q4[3] & 0xffff0000u)}; }
;                     else { r0 = bb[mm][bj][0]; r1 = bb[mm][bj][1]; }
;                     const f32x4 h0 = r0 + gv[bj][0] * (acc[ai][bj][m][0] + bv[bj][0]), h1 = r1 + gv[bj][1] * (acc[ai][bj][m][1] + bv[bj][1]);
;                     { u32x4 w; w.x = cvt_pk_bf16(h0[0], h0[1]); w.y = cvt_pk_bf16(h0[2], h0[3]); w.z = cvt_pk_bf16(h1[0], h1[1]); w.w = cvt_pk_bf16(h1[2], h1[3]); ST16(1, Hc + (size_t)(e * 2u), w); }
;                     if (FUSE) { ssum += ((h0[0] * h0[0] + h0[1] * h0[1]) + (h0[2] * h0[2] + h0[3] * h0[3])) + ((h1[0] * h1[0] + h1[1] * h1[1]) + (h1[2] * h1[2] + h1[3] * h1[3]));
;                         const f32x4 z0 = h0 * wv[bj][0], z1 = h1 * wv[bj][1];
;                         u32x4 w; w.x = cvt_pk_bf16(z0[0], z0[1]); w.y = cvt_pk_bf16(z0[2], z0[3]); w.z = cvt_pk_bf16(z1[0], z1[1]); w.w = cvt_pk_bf16(z1[2], z1[3]);
.LBB0_892:
	s_or_b64 exec, exec, s[24:25]
	v_add_u32_e32 v57, 0x10000, v196
	v_add_u32_e32 v153, 0x10100, v196
	v_add_u32_e32 v136, 0x18000, v196
	v_add_u32_e32 v152, 0x18100, v196
	s_waitcnt lgkmcnt(0)
	s_waitcnt vmcnt(8)
	v_mov_b64_e32 v[154:155], v[238:239]
	v_mov_b64_e32 v[156:157], v[240:241]
	v_mov_b64_e32 v[158:159], v[242:243]
	v_mov_b64_e32 v[160:161], v[244:245]
	v_mov_b64_e32 v[20:21], v[246:247]
	v_mov_b64_e32 v[22:23], v[248:249]
	v_mov_b64_e32 v[16:17], v[250:251]
	v_mov_b64_e32 v[18:19], v[254:255]
	v_add_u32_e32 v252, 0x40000, v196
	global_load_dwordx4 v[238:241], v252, s[14:15]
	global_load_dwordx4 v[242:245], v252, s[14:15] offset:256
	v_add_u32_e32 v252, 0x48000, v196
	global_load_dwordx4 v[246:249], v252, s[14:15]
	global_load_dwordx2 v[250:251], v252, s[14:15] offset:256
	global_load_dwordx2 v[254:255], v252, s[14:15] offset:264
	s_nop 0
	v_lshlrev_b32_e32 v162, 16, v154
	v_and_b32_e32 v163, 0xffff0000, v154
	v_lshlrev_b32_e32 v154, 16, v155
	v_and_b32_e32 v155, 0xffff0000, v155
	v_lshlrev_b32_e32 v164, 16, v156
	v_and_b32_e32 v165, 0xffff0000, v156
	v_lshlrev_b32_e32 v156, 16, v157
	v_and_b32_e32 v157, 0xffff0000, v157
	s_nop 0
	v_lshlrev_b32_e32 v166, 16, v158
	v_and_b32_e32 v167, 0xffff0000, v158
	v_lshlrev_b32_e32 v158, 16, v159
	v_and_b32_e32 v159, 0xffff0000, v159
	v_lshlrev_b32_e32 v170, 16, v160
	v_and_b32_e32 v171, 0xffff0000, v160
	v_lshlrev_b32_e32 v160, 16, v161
	v_and_b32_e32 v161, 0xffff0000, v161
	v_pk_fma_f32 v[154:155], v[122:123], v[14:15], v[154:155]
	v_pk_fma_f32 v[162:163], v[124:125], v[12:13], v[162:163]
	v_pk_fma_f32 v[126:127], v[126:127], v[10:11], v[156:157]
	v_pk_fma_f32 v[142:143], v[142:143], v[8:9], v[164:165]
	v_pk_fma_f32 v[150:151], v[150:151], v[6:7], v[158:159]
	v_pk_fma_f32 v[148:149], v[148:149], v[4:5], v[166:167]
	v_pk_fma_f32 v[146:147], v[146:147], v[2:3], v[160:161]
	v_pk_fma_f32 v[144:145], v[144:145], v[0:1], v[170:171]
	v_cvt_pk_bf16_f32 v122, v162, v163
	v_cvt_pk_bf16_f32 v123, v154, v155
	v_cvt_pk_bf16_f32 v124, v142, v143
	v_cvt_pk_bf16_f32 v125, v126, v127
	v_mul_f32_e32 v166, v163, v163
	v_mul_f32_e32 v167, v155, v155
	v_mul_f32_e32 v170, v143, v143
	v_mul_f32_e32 v171, v127, v127
	v_pk_mul_f32 v[156:157], v[102:103], v[154:155]
	v_pk_mul_f32 v[158:159], v[104:105], v[162:163]
	v_pk_mul_f32 v[160:161], v[98:99], v[126:127]
	v_pk_mul_f32 v[164:165], v[100:101], v[142:143]
	v_mul_f32_e32 v127, v149, v149
	v_mul_f32_e32 v143, v151, v151
	v_mul_f32_e32 v155, v145, v145
	v_mul_f32_e32 v163, v147, v147
	v_fmac_f32_e32 v166, v162, v162
	v_fmac_f32_e32 v167, v154, v154
	v_fmac_f32_e32 v170, v142, v142
	v_fmac_f32_e32 v171, v126, v126
	v_fmac_f32_e32 v127, v148, v148
	v_fmac_f32_e32 v143, v150, v150
	v_fmac_f32_e32 v155, v144, v144
	v_fmac_f32_e32 v163, v146, v146
	global_store_dwordx4 v57, v[122:125], s[14:15]
	v_add_f32_e32 v126, v166, v167
	v_add_f32_e32 v142, v170, v171
	v_cvt_pk_bf16_f32 v122, v158, v159
	v_cvt_pk_bf16_f32 v123, v156, v157
	v_cvt_pk_bf16_f32 v124, v164, v165
	v_cvt_pk_bf16_f32 v125, v160, v161
	global_store_dwordx4 v57, v[122:125], s[86:87]
	v_add_f32_e32 v57, v127, v143
	v_add_f32_e32 v127, v155, v163
	v_add_f32_e32 v126, v126, v142
	v_add_f32_e32 v57, v57, v127
	v_cvt_pk_bf16_f32 v122, v148, v149
	v_cvt_pk_bf16_f32 v123, v150, v151
	v_cvt_pk_bf16_f32 v124, v144, v145
	v_cvt_pk_bf16_f32 v125, v146, v147
	v_add_f32_e32 v57, v126, v57
	global_store_dwordx4 v153, v[122:125], s[14:15]
	ds_bpermute_b32 v125, v168, v57
	v_pk_mul_f32 v[126:127], v[80:81], v[150:151]
	v_pk_mul_f32 v[122:123], v[82:83], v[148:149]
	v_pk_mul_f32 v[142:143], v[74:75], v[146:147]
	v_cvt_pk_bf16_f32 v124, v122, v123
	s_waitcnt lgkmcnt(0)
	v_add_f32_e32 v57, v57, v125
	ds_bpermute_b32 v122, v169, v57
	v_pk_mul_f32 v[144:145], v[76:77], v[144:145]
	v_cvt_pk_bf16_f32 v125, v126, v127
	s_nop 0
	v_cvt_pk_bf16_f32 v126, v144, v145
	v_cvt_pk_bf16_f32 v127, v142, v143
	global_store_dwordx4 v153, v[124:127], s[86:87]
	s_and_saveexec_b64 s[24:25], s[0:1]
	s_cbranch_execz .LBB0_894
	v_or_b32_e32 v124, 32, v56
	v_mov_b32_e32 v125, v137
	v_lshl_add_u64 v[124:125], v[124:125], 2, s[12:13]
	s_waitcnt lgkmcnt(0)
	v_add_f32_e32 v57, v57, v122
	global_atomic_add_f32 v[124:125], v57, off
.LBB0_894:
	s_or_b64 exec, exec, s[24:25]
	s_nop 0
	v_lshlrev_b32_e32 v126, 16, v20
	v_and_b32_e32 v127, 0xffff0000, v20
	v_lshlrev_b32_e32 v20, 16, v21
	v_and_b32_e32 v21, 0xffff0000, v21
	s_waitcnt lgkmcnt(0)
;     __device__ __forceinline__ void operator()(const f32x4 (&acc)[2][2][4][2], const Unit& u, int wr, int wc, int fr, int fq) const {
;     ...
;         for (int rg = 0; rg < 8 / RGB; ++rg) {
;             u32x4 braw[INPLACE ? RGB : 1][2]; f32x4 bb[INPLACE ? 1 : RGB][2][2];
; #pragma unroll
;             for (int mm = 0; mm < RGB; ++mm) { const int q = rg * RGB + mm, ai = q >> 2, m = q & 3;
; #pragma unroll
;                 for (int bj = 0; bj < 2; ++bj) { const unsigned e = e0 + (unsigned)((ai * 128 + m * 16) * D + bj * 128);
;                     if constexpr (INPLACE) braw[mm][bj] = *(const u32x4*)(Hc + (size_t)(e * 2u));
;                     else { bb[mm][bj][0] = *(const f32x4*)(bsc + (size_t)(e * 4u)); bb[mm][bj][1] = *(const f32x4*)(bsc + (size_t)(e * 4u + 16u)); } } }
; #pragma unroll
;             for (int mm = 0; mm < RGB; ++mm) { const int q = rg * RGB + mm, ai = q >> 2, m = q & 3; float ssum = 0.f;
; #pragma unroll
;                 for (int bj = 0; bj < 2; ++bj) { const unsigned e = e0 + (unsigned)((ai * 128 + m * 16) * D + bj * 128);
;                     f32x4 r0, r1;
;                     if constexpr (INPLACE) { const u32x4 q4 = braw[mm][bj];
;                         r0 = (f32x4){__uint_as_float(q4[0] << 16), __uint_as_float(q4[0] & 0xffff0000u), __uint_as_float(q4[1] << 16), __uint_as_float(q4[1] & 0xffff0000u)};
;                         r1 = (f32x4){__uint_as_float(q4[2] << 16), __uint_as_float(q4[2] & 0xffff0000u), __uint_as_float(q4[3] << 16), __uint_as_float(q4[3] & 0xffff0000u)}; }
;                     else { r0 = bb[mm][bj][0]; r1 = bb[mm][bj][1]; }
;                     const f32x4 h0 = r0 + gv[bj][0] * (acc[ai][bj][m][0] + bv[bj][0]), h1 = r1 + gv[bj][1] * (acc[ai][bj][m][1] + bv[bj][1]);
;                     { u32x4 w; w.x = cvt_pk_bf16(h0[0], h0[1]); w.y = cvt_pk_bf16(h0[2], h0[3]); w.z = cvt_pk_bf16(h1[0], h1[1]); w.w = cvt_pk_bf16(h1[2], h1[3]); ST16(1, Hc + (size_t)(e * 2u), w); }
;                     if (FUSE) { ssum += ((h0[0] * h0[0] + h0[1] * h0[1]) + (h0[2] * h0[2] + h0[3] * h0[3])) + ((h1[0] * h1[0] + h1[1] * h1[1]) + (h1[2] * h1[2] + h1[3] * h1[3]));
;                         const f32x4 z0 = h0 * wv[bj][0], z1 = h1 * wv[bj][1];
;                         u32x4 w; w.x = cvt_pk_bf16(z0[0], z0[1]); w.y = cvt_pk_bf16(z0[2], z0[3]); w.z = cvt_pk_bf16(z1[0], z1[1]); w.w = cvt_pk_bf16(z1[2], z1[3]);
	v_lshl_add_u64 v[122:123], s[14:15], 0, v[136:137]
	v_lshlrev_b32_e32 v142, 16, v22
	v_and_b32_e32 v143, 0xffff0000, v22
	v_lshlrev_b32_e32 v22, 16, v23
	v_and_b32_e32 v23, 0xffff0000, v23
	v_pk_fma_f32 v[120:121], v[120:121], v[14:15], v[20:21]
	v_pk_fma_f32 v[118:119], v[118:119], v[12:13], v[126:127]
	v_pk_fma_f32 v[116:117], v[116:117], v[10:11], v[22:23]
	v_cvt_pk_bf16_f32 v20, v118, v119
	v_cvt_pk_bf16_f32 v21, v120, v121
	v_pk_fma_f32 v[114:115], v[114:115], v[8:9], v[142:143]
	v_mov_b32_e32 v153, v137
	v_cvt_pk_bf16_f32 v22, v114, v115
	v_cvt_pk_bf16_f32 v23, v116, v117
	global_store_dwordx4 v[122:123], v[20:23], off
	v_lshl_add_u64 v[124:125], s[14:15], 0, v[152:153]
	s_nop 0
	v_mul_f32_e32 v20, v119, v119
	v_mul_f32_e32 v21, v121, v121
	v_fmac_f32_e32 v20, v118, v118
	v_fmac_f32_e32 v21, v120, v120
	v_add_f32_e32 v20, v20, v21
	v_mul_f32_e32 v21, v115, v115
	v_mul_f32_e32 v22, v117, v117
	v_fmac_f32_e32 v21, v114, v114
	v_fmac_f32_e32 v22, v116, v116
	v_add_f32_e32 v21, v21, v22
	v_add_f32_e32 v57, v20, v21
	v_pk_mul_f32 v[22:23], v[102:103], v[120:121]
	v_pk_mul_f32 v[20:21], v[104:105], v[118:119]
	v_pk_mul_f32 v[114:115], v[100:101], v[114:115]
	v_cvt_pk_bf16_f32 v20, v20, v21
	v_cvt_pk_bf16_f32 v21, v22, v23
	v_pk_mul_f32 v[116:117], v[98:99], v[116:117]
	v_cvt_pk_bf16_f32 v22, v114, v115
	v_lshl_add_u64 v[114:115], s[86:87], 0, v[136:137]
	v_cvt_pk_bf16_f32 v23, v116, v117
	global_store_dwordx4 v[114:115], v[20:23], off
	s_nop 0
	s_nop 0
	v_lshlrev_b32_e32 v20, 16, v16
	v_and_b32_e32 v21, 0xffff0000, v16
	v_lshlrev_b32_e32 v16, 16, v17
	v_and_b32_e32 v17, 0xffff0000, v17
	v_lshlrev_b32_e32 v22, 16, v18
	v_and_b32_e32 v23, 0xffff0000, v18
	v_lshlrev_b32_e32 v18, 16, v19
	v_and_b32_e32 v19, 0xffff0000, v19
	v_pk_fma_f32 v[112:113], v[112:113], v[6:7], v[16:17]
	v_pk_fma_f32 v[20:21], v[110:111], v[4:5], v[20:21]
	v_pk_fma_f32 v[108:109], v[108:109], v[2:3], v[18:19]
	v_cvt_pk_bf16_f32 v16, v20, v21
	v_cvt_pk_bf16_f32 v17, v112, v113
	v_pk_fma_f32 v[22:23], v[106:107], v[0:1], v[22:23]
	v_pk_mul_f32 v[106:107], v[74:75], v[108:109]
	v_cvt_pk_bf16_f32 v18, v22, v23
	v_cvt_pk_bf16_f32 v19, v108, v109
	global_store_dwordx4 v[124:125], v[16:19], off
	s_nop 1
	v_mul_f32_e32 v16, v21, v21
	v_mul_f32_e32 v17, v113, v113
	v_fmac_f32_e32 v16, v20, v20
	v_fmac_f32_e32 v17, v112, v112
	v_add_f32_e32 v16, v16, v17
	v_mul_f32_e32 v17, v23, v23
	v_mul_f32_e32 v18, v109, v109
	v_fmac_f32_e32 v17, v22, v22
	v_fmac_f32_e32 v18, v108, v108
	v_add_f32_e32 v17, v17, v18
	v_add_f32_e32 v16, v16, v17
	v_add_f32_e32 v57, v57, v16
	ds_bpermute_b32 v110, v168, v57
	v_pk_mul_f32 v[16:17], v[80:81], v[112:113]
	v_pk_mul_f32 v[18:19], v[82:83], v[20:21]
	v_pk_mul_f32 v[20:21], v[76:77], v[22:23]
	v_cvt_pk_bf16_f32 v18, v18, v19
	v_cvt_pk_bf16_f32 v19, v16, v17
	s_waitcnt lgkmcnt(0)
	v_add_f32_e32 v16, v57, v110
	ds_bpermute_b32 v17, v169, v16
	v_lshl_add_u64 v[22:23], s[86:87], 0, v[152:153]
	v_cvt_pk_bf16_f32 v20, v20, v21
	v_cvt_pk_bf16_f32 v21, v106, v107
	global_store_dwordx4 v[22:23], v[18:21], off
	s_and_saveexec_b64 s[24:25], s[0:1]
	s_cbranch_execz .LBB0_896
	v_or_b32_e32 v136, 48, v56
	v_lshl_add_u64 v[18:19], v[136:137], 2, s[12:13]
	s_waitcnt lgkmcnt(0)
	v_add_f32_e32 v16, v16, v17
	global_atomic_add_f32 v[18:19], v16, off
.LBB0_896:
	s_or_b64 exec, exec, s[24:25]
	v_add_u32_e32 v57, 0x40000, v196
	v_add_u32_e32 v107, 0x40100, v196
	v_add_u32_e32 v136, 0x48000, v196
	v_add_u32_e32 v106, 0x48100, v196
	s_waitcnt lgkmcnt(0)
	s_waitcnt vmcnt(8)
	v_mov_b64_e32 v[108:109], v[238:239]
	v_mov_b64_e32 v[110:111], v[240:241]
	v_mov_b64_e32 v[112:113], v[242:243]
	v_mov_b64_e32 v[114:115], v[244:245]
	v_mov_b64_e32 v[20:21], v[246:247]
	v_mov_b64_e32 v[22:23], v[248:249]
	v_mov_b64_e32 v[16:17], v[250:251]
	v_mov_b64_e32 v[18:19], v[254:255]
	v_add_u32_e32 v252, 0x50000, v196
	global_load_dwordx4 v[238:241], v252, s[14:15]
	global_load_dwordx4 v[242:245], v252, s[14:15] offset:256
	v_add_u32_e32 v252, 0x58000, v196
	global_load_dwordx4 v[246:249], v252, s[14:15]
	global_load_dwordx2 v[250:251], v252, s[14:15] offset:256
	global_load_dwordx2 v[254:255], v252, s[14:15] offset:264
	s_nop 0
	v_lshlrev_b32_e32 v116, 16, v108
	v_and_b32_e32 v117, 0xffff0000, v108
	v_lshlrev_b32_e32 v108, 16, v109
	v_and_b32_e32 v109, 0xffff0000, v109
	v_lshlrev_b32_e32 v118, 16, v110
	v_and_b32_e32 v119, 0xffff0000, v110
	v_lshlrev_b32_e32 v110, 16, v111
	v_and_b32_e32 v111, 0xffff0000, v111
	s_nop 0
	v_lshlrev_b32_e32 v120, 16, v112
	v_and_b32_e32 v121, 0xffff0000, v112
	v_lshlrev_b32_e32 v112, 16, v113
	v_and_b32_e32 v113, 0xffff0000, v113
	v_lshlrev_b32_e32 v122, 16, v114
	v_and_b32_e32 v123, 0xffff0000, v114
	v_lshlrev_b32_e32 v114, 16, v115
	v_and_b32_e32 v115, 0xffff0000, v115
	v_pk_fma_f32 v[78:79], v[78:79], v[14:15], v[108:109]
	v_pk_fma_f32 v[108:109], v[84:85], v[12:13], v[116:117]
	v_pk_fma_f32 v[110:111], v[86:87], v[10:11], v[110:111]
	v_pk_fma_f32 v[88:89], v[88:89], v[8:9], v[118:119]
	v_pk_fma_f32 v[96:97], v[96:97], v[6:7], v[112:113]
	v_pk_fma_f32 v[94:95], v[94:95], v[4:5], v[120:121]
	v_pk_fma_f32 v[92:93], v[92:93], v[2:3], v[114:115]
	v_pk_fma_f32 v[90:91], v[90:91], v[0:1], v[122:123]
	v_cvt_pk_bf16_f32 v84, v108, v109
	v_cvt_pk_bf16_f32 v85, v78, v79
	v_cvt_pk_bf16_f32 v86, v88, v89
	v_cvt_pk_bf16_f32 v87, v110, v111
	v_mul_f32_e32 v120, v109, v109
	v_mul_f32_e32 v121, v79, v79
	v_mul_f32_e32 v122, v89, v89
	v_mul_f32_e32 v123, v111, v111
	v_pk_mul_f32 v[112:113], v[102:103], v[78:79]
	v_pk_mul_f32 v[114:115], v[104:105], v[108:109]
	v_pk_mul_f32 v[116:117], v[98:99], v[110:111]
	v_pk_mul_f32 v[118:119], v[100:101], v[88:89]
	v_mul_f32_e32 v79, v95, v95
	v_mul_f32_e32 v89, v97, v97
	v_mul_f32_e32 v109, v91, v91
	v_mul_f32_e32 v111, v93, v93
	v_fmac_f32_e32 v120, v108, v108
	v_fmac_f32_e32 v121, v78, v78
	v_fmac_f32_e32 v122, v88, v88
	v_fmac_f32_e32 v123, v110, v110
	v_fmac_f32_e32 v79, v94, v94
	v_fmac_f32_e32 v89, v96, v96
	v_fmac_f32_e32 v109, v90, v90
	v_fmac_f32_e32 v111, v92, v92
	global_store_dwordx4 v57, v[84:87], s[14:15]
	v_add_f32_e32 v78, v120, v121
	v_add_f32_e32 v88, v122, v123
	v_cvt_pk_bf16_f32 v84, v114, v115
	v_cvt_pk_bf16_f32 v85, v112, v113
	v_cvt_pk_bf16_f32 v86, v118, v119
	v_cvt_pk_bf16_f32 v87, v116, v117
	global_store_dwordx4 v57, v[84:87], s[86:87]
	v_add_f32_e32 v57, v79, v89
	v_add_f32_e32 v79, v109, v111
	v_add_f32_e32 v78, v78, v88
	v_add_f32_e32 v57, v57, v79
	v_cvt_pk_bf16_f32 v84, v94, v95
	v_cvt_pk_bf16_f32 v85, v96, v97
	v_add_f32_e32 v57, v78, v57
	v_cvt_pk_bf16_f32 v86, v90, v91
	v_cvt_pk_bf16_f32 v87, v92, v93
	global_store_dwordx4 v107, v[84:87], s[14:15]
	ds_bpermute_b32 v85, v168, v57
	v_pk_mul_f32 v[78:79], v[82:83], v[94:95]
	v_pk_mul_f32 v[86:87], v[80:81], v[96:97]
	v_cvt_pk_bf16_f32 v84, v78, v79
	v_pk_mul_f32 v[88:89], v[74:75], v[92:93]
	s_waitcnt lgkmcnt(0)
;     __device__ __forceinline__ void operator()(const f32x4 (&acc)[2][2][4][2], const Unit& u, int wr, int wc, int fr, int fq) const {
;     ...
;         for (int rg = 0; rg < 8 / RGB; ++rg) {
;             u32x4 braw[INPLACE ? RGB : 1][2]; f32x4 bb[INPLACE ? 1 : RGB][2][2];
; #pragma unroll
;             for (int mm = 0; mm < RGB; ++mm) { const int q = rg * RGB + mm, ai = q >> 2, m = q & 3;
; #pragma unroll
;                 for (int bj = 0; bj < 2; ++bj) { const unsigned e = e0 + (unsigned)((ai * 128 + m * 16) * D + bj * 128);
;                     if constexpr (INPLACE) braw[mm][bj] = *(const u32x4*)(Hc + (size_t)(e * 2u));
;                     else { bb[mm][bj][0] = *(const f32x4*)(bsc + (size_t)(e * 4u)); bb[mm][bj][1] = *(const f32x4*)(bsc + (size_t)(e * 4u + 16u)); } } }
; #pragma unroll
;             for (int mm = 0; mm < RGB; ++mm) { const int q = rg * RGB + mm, ai = q >> 2, m = q & 3; float ssum = 0.f;
; #pragma unroll
;                 for (int bj = 0; bj < 2; ++bj) { const unsigned e = e0 + (unsigned)((ai * 128 + m * 16) * D + bj * 128);
;                     f32x4 r0, r1;
;                     if constexpr (INPLACE) { const u32x4 q4 = braw[mm][bj];
;                         r0 = (f32x4){__uint_as_float(q4[0] << 16), __uint_as_float(q4[0] & 0xffff0000u), __uint_as_float(q4[1] << 16), __uint_as_float(q4[1] & 0xffff0000u)};
;                         r1 = (f32x4){__uint_as_float(q4[2] << 16), __uint_as_float(q4[2] & 0xffff0000u), __uint_as_float(q4[3] << 16), __uint_as_float(q4[3] & 0xffff0000u)}; }
;                     else { r0 = bb[mm][bj][0]; r1 = bb[mm][bj][1]; }
;                     const f32x4 h0 = r0 + gv[bj][0] * (acc[ai][bj][m][0] + bv[bj][0]), h1 = r1 + gv[bj][1] * (acc[ai][bj][m][1] + bv[bj][1]);
;                     { u32x4 w; w.x = cvt_pk_bf16(h0[0], h0[1]); w.y = cvt_pk_bf16(h0[2], h0[3]); w.z = cvt_pk_bf16(h1[0], h1[1]); w.w = cvt_pk_bf16(h1[2], h1[3]); ST16(1, Hc + (size_t)(e * 2u), w); }
;                     if (FUSE) { ssum += ((h0[0] * h0[0] + h0[1] * h0[1]) + (h0[2] * h0[2] + h0[3] * h0[3])) + ((h1[0] * h1[0] + h1[1] * h1[1]) + (h1[2] * h1[2] + h1[3] * h1[3]));
;                         const f32x4 z0 = h0 * wv[bj][0], z1 = h1 * wv[bj][1];
;                         u32x4 w; w.x = cvt_pk_bf16(z0[0], z0[1]); w.y = cvt_pk_bf16(z0[2], z0[3]); w.z = cvt_pk_bf16(z1[0], z1[1]); w.w = cvt_pk_bf16(z1[2], z1[3]);
	v_add_f32_e32 v57, v57, v85
	ds_bpermute_b32 v78, v169, v57
	v_pk_mul_f32 v[90:91], v[76:77], v[90:91]
	v_cvt_pk_bf16_f32 v85, v86, v87
	s_nop 0
	v_cvt_pk_bf16_f32 v86, v90, v91
	v_cvt_pk_bf16_f32 v87, v88, v89
	global_store_dwordx4 v107, v[84:87], s[86:87]
	s_and_saveexec_b64 s[24:25], s[0:1]
	s_cbranch_execz .LBB0_898
	v_add_u32_e32 v84, 0x80, v56
	v_mov_b32_e32 v85, v137
	v_lshl_add_u64 v[84:85], v[84:85], 2, s[12:13]
	s_waitcnt lgkmcnt(0)
	v_add_f32_e32 v57, v57, v78
	global_atomic_add_f32 v[84:85], v57, off
.LBB0_898:
	s_or_b64 exec, exec, s[24:25]
	s_nop 0
	v_lshlrev_b32_e32 v86, 16, v20
	v_and_b32_e32 v87, 0xffff0000, v20
	v_lshlrev_b32_e32 v20, 16, v21
	v_and_b32_e32 v21, 0xffff0000, v21
	s_waitcnt lgkmcnt(0)
	v_lshl_add_u64 v[78:79], s[14:15], 0, v[136:137]
	v_lshlrev_b32_e32 v88, 16, v22
	v_and_b32_e32 v89, 0xffff0000, v22
	v_lshlrev_b32_e32 v22, 16, v23
	v_and_b32_e32 v23, 0xffff0000, v23
	v_pk_fma_f32 v[72:73], v[72:73], v[14:15], v[20:21]
	v_pk_fma_f32 v[70:71], v[70:71], v[12:13], v[86:87]
	v_pk_fma_f32 v[68:69], v[68:69], v[10:11], v[22:23]
	v_cvt_pk_bf16_f32 v20, v70, v71
	v_cvt_pk_bf16_f32 v21, v72, v73
	v_pk_fma_f32 v[66:67], v[66:67], v[8:9], v[88:89]
	v_mov_b32_e32 v107, v137
	v_cvt_pk_bf16_f32 v22, v66, v67
	v_cvt_pk_bf16_f32 v23, v68, v69
	global_store_dwordx4 v[78:79], v[20:23], off
	v_lshl_add_u64 v[84:85], s[14:15], 0, v[106:107]
	s_nop 0
	v_mul_f32_e32 v20, v71, v71
	v_mul_f32_e32 v21, v73, v73
	v_fmac_f32_e32 v20, v70, v70
	v_fmac_f32_e32 v21, v72, v72
	v_add_f32_e32 v20, v20, v21
	v_mul_f32_e32 v21, v67, v67
	v_mul_f32_e32 v22, v69, v69
	v_fmac_f32_e32 v21, v66, v66
	v_fmac_f32_e32 v22, v68, v68
	v_add_f32_e32 v21, v21, v22
	v_add_f32_e32 v57, v20, v21
	v_pk_mul_f32 v[22:23], v[102:103], v[72:73]
	v_pk_mul_f32 v[20:21], v[104:105], v[70:71]
	v_pk_mul_f32 v[66:67], v[100:101], v[66:67]
	v_cvt_pk_bf16_f32 v20, v20, v21
	v_cvt_pk_bf16_f32 v21, v22, v23
	v_pk_mul_f32 v[68:69], v[98:99], v[68:69]
	v_cvt_pk_bf16_f32 v22, v66, v67
	v_lshl_add_u64 v[66:67], s[86:87], 0, v[136:137]
	v_cvt_pk_bf16_f32 v23, v68, v69
	global_store_dwordx4 v[66:67], v[20:23], off
	s_nop 0
	s_nop 0
	v_lshlrev_b32_e32 v20, 16, v16
	v_and_b32_e32 v21, 0xffff0000, v16
	v_lshlrev_b32_e32 v16, 16, v17
	v_and_b32_e32 v17, 0xffff0000, v17
	v_lshlrev_b32_e32 v22, 16, v18
	v_and_b32_e32 v23, 0xffff0000, v18
	v_lshlrev_b32_e32 v18, 16, v19
	v_and_b32_e32 v19, 0xffff0000, v19
	v_pk_fma_f32 v[64:65], v[64:65], v[6:7], v[16:17]
	v_pk_fma_f32 v[20:21], v[62:63], v[4:5], v[20:21]
	v_pk_fma_f32 v[60:61], v[60:61], v[2:3], v[18:19]
	v_cvt_pk_bf16_f32 v16, v20, v21
	v_cvt_pk_bf16_f32 v17, v64, v65
	v_pk_fma_f32 v[22:23], v[58:59], v[0:1], v[22:23]
	v_pk_mul_f32 v[58:59], v[74:75], v[60:61]
	v_cvt_pk_bf16_f32 v18, v22, v23
	v_cvt_pk_bf16_f32 v19, v60, v61
	global_store_dwordx4 v[84:85], v[16:19], off
	s_nop 1
	v_mul_f32_e32 v16, v21, v21
	v_mul_f32_e32 v17, v65, v65
	v_fmac_f32_e32 v16, v20, v20
	v_fmac_f32_e32 v17, v64, v64
	v_add_f32_e32 v16, v16, v17
	v_mul_f32_e32 v17, v23, v23
	v_mul_f32_e32 v18, v61, v61
	v_fmac_f32_e32 v17, v22, v22
	v_fmac_f32_e32 v18, v60, v60
	v_add_f32_e32 v17, v17, v18
	v_add_f32_e32 v16, v16, v17
	v_add_f32_e32 v57, v57, v16
	ds_bpermute_b32 v62, v168, v57
	v_pk_mul_f32 v[16:17], v[80:81], v[64:65]
	v_pk_mul_f32 v[18:19], v[82:83], v[20:21]
	v_pk_mul_f32 v[20:21], v[76:77], v[22:23]
	v_cvt_pk_bf16_f32 v18, v18, v19
	v_cvt_pk_bf16_f32 v19, v16, v17
	s_waitcnt lgkmcnt(0)
	v_add_f32_e32 v16, v57, v62
	ds_bpermute_b32 v17, v169, v16
	v_lshl_add_u64 v[22:23], s[86:87], 0, v[106:107]
	v_cvt_pk_bf16_f32 v20, v20, v21
	v_cvt_pk_bf16_f32 v21, v58, v59
	global_store_dwordx4 v[22:23], v[18:21], off
	s_and_saveexec_b64 s[24:25], s[0:1]
	s_cbranch_execz .LBB0_900
	v_add_u32_e32 v136, 0x90, v56
	v_lshl_add_u64 v[18:19], v[136:137], 2, s[12:13]
	s_waitcnt lgkmcnt(0)
	v_add_f32_e32 v16, v16, v17
	global_atomic_add_f32 v[18:19], v16, off
;     __device__ __forceinline__ void operator()(const f32x4 (&acc)[2][2][4][2], const Unit& u, int wr, int wc, int fr, int fq) const {
;     ...
;         for (int rg = 0; rg < 8 / RGB; ++rg) {
;             u32x4 braw[INPLACE ? RGB : 1][2]; f32x4 bb[INPLACE ? 1 : RGB][2][2];
; #pragma unroll
;             for (int mm = 0; mm < RGB; ++mm) { const int q = rg * RGB + mm, ai = q >> 2, m = q & 3;
; #pragma unroll
;                 for (int bj = 0; bj < 2; ++bj) { const unsigned e = e0 + (unsigned)((ai * 128 + m * 16) * D + bj * 128);
;                     if constexpr (INPLACE) braw[mm][bj] = *(const u32x4*)(Hc + (size_t)(e * 2u));
;                     else { bb[mm][bj][0] = *(const f32x4*)(bsc + (size_t)(e * 4u)); bb[mm][bj][1] = *(const f32x4*)(bsc + (size_t)(e * 4u + 16u)); } } }
; #pragma unroll
;             for (int mm = 0; mm < RGB; ++mm) { const int q = rg * RGB + mm, ai = q >> 2, m = q & 3; float ssum = 0.f;
; #pragma unroll
;                 for (int bj = 0; bj < 2; ++bj) { const unsigned e = e0 + (unsigned)((ai * 128 + m * 16) * D + bj * 128);
;                     f32x4 r0, r1;
;                     if constexpr (INPLACE) { const u32x4 q4 = braw[mm][bj];
;                         r0 = (f32x4){__uint_as_float(q4[0] << 16), __uint_as_float(q4[0] & 0xffff0000u), __uint_as_float(q4[1] << 16), __uint_as_float(q4[1] & 0xffff0000u)};
;                         r1 = (f32x4){__uint_as_float(q4[2] << 16), __uint_as_float(q4[2] & 0xffff0000u), __uint_as_float(q4[3] << 16), __uint_as_float(q4[3] & 0xffff0000u)}; }
;                     else { r0 = bb[mm][bj][0]; r1 = bb[mm][bj][1]; }
;                     const f32x4 h0 = r0 + gv[bj][0] * (acc[ai][bj][m][0] + bv[bj][0]), h1 = r1 + gv[bj][1] * (acc[ai][bj][m][1] + bv[bj][1]);
;                     { u32x4 w; w.x = cvt_pk_bf16(h0[0], h0[1]); w.y = cvt_pk_bf16(h0[2], h0[3]); w.z = cvt_pk_bf16(h1[0], h1[1]); w.w = cvt_pk_bf16(h1[2], h1[3]); ST16(1, Hc + (size_t)(e * 2u), w); }
;                     if (FUSE) { ssum += ((h0[0] * h0[0] + h0[1] * h0[1]) + (h0[2] * h0[2] + h0[3] * h0[3])) + ((h1[0] * h1[0] + h1[1] * h1[1]) + (h1[2] * h1[2] + h1[3] * h1[3]));
;                         const f32x4 z0 = h0 * wv[bj][0], z1 = h1 * wv[bj][1];
;                         u32x4 w; w.x = cvt_pk_bf16(z0[0], z0[1]); w.y = cvt_pk_bf16(z0[2], z0[3]); w.z = cvt_pk_bf16(z1[0], z1[1]); w.w = cvt_pk_bf16(z1[2], z1[3]);
.LBB0_900:
	s_or_b64 exec, exec, s[24:25]
	v_add_u32_e32 v57, 0x50000, v196
	v_add_u32_e32 v59, 0x50100, v196
	v_add_u32_e32 v136, 0x58000, v196
	v_add_u32_e32 v58, 0x58100, v196
	s_waitcnt lgkmcnt(0)
	s_waitcnt vmcnt(8)
	v_mov_b64_e32 v[60:61], v[238:239]
	v_mov_b64_e32 v[62:63], v[240:241]
	v_mov_b64_e32 v[64:65], v[242:243]
	v_mov_b64_e32 v[66:67], v[244:245]
	v_mov_b64_e32 v[20:21], v[246:247]
	v_mov_b64_e32 v[22:23], v[248:249]
	v_mov_b64_e32 v[16:17], v[250:251]
	v_mov_b64_e32 v[18:19], v[254:255]
	s_nop 0
	v_lshlrev_b32_e32 v68, 16, v60
	v_and_b32_e32 v69, 0xffff0000, v60
	v_lshlrev_b32_e32 v60, 16, v61
	v_and_b32_e32 v61, 0xffff0000, v61
	v_lshlrev_b32_e32 v70, 16, v62
	v_and_b32_e32 v71, 0xffff0000, v62
	v_lshlrev_b32_e32 v62, 16, v63
	v_and_b32_e32 v63, 0xffff0000, v63
	s_nop 0
	v_lshlrev_b32_e32 v72, 16, v64
	v_and_b32_e32 v73, 0xffff0000, v64
	v_lshlrev_b32_e32 v64, 16, v65
	v_and_b32_e32 v65, 0xffff0000, v65
	v_lshlrev_b32_e32 v78, 16, v66
	v_and_b32_e32 v79, 0xffff0000, v66
	v_lshlrev_b32_e32 v66, 16, v67
	v_and_b32_e32 v67, 0xffff0000, v67
	v_pk_fma_f32 v[60:61], v[42:43], v[14:15], v[60:61]
	v_pk_fma_f32 v[68:69], v[40:41], v[12:13], v[68:69]
	v_pk_fma_f32 v[44:45], v[44:45], v[10:11], v[62:63]
	v_pk_fma_f32 v[46:47], v[46:47], v[8:9], v[70:71]
	v_pk_fma_f32 v[54:55], v[54:55], v[6:7], v[64:65]
	v_pk_fma_f32 v[52:53], v[52:53], v[4:5], v[72:73]
	v_pk_fma_f32 v[50:51], v[50:51], v[2:3], v[66:67]
	v_pk_fma_f32 v[48:49], v[48:49], v[0:1], v[78:79]
	v_cvt_pk_bf16_f32 v40, v68, v69
	v_cvt_pk_bf16_f32 v41, v60, v61
	v_cvt_pk_bf16_f32 v42, v46, v47
	v_cvt_pk_bf16_f32 v43, v44, v45
	v_mul_f32_e32 v72, v69, v69
	v_mul_f32_e32 v73, v61, v61
	v_mul_f32_e32 v78, v47, v47
	v_mul_f32_e32 v79, v45, v45
	v_pk_mul_f32 v[62:63], v[102:103], v[60:61]
	v_pk_mul_f32 v[64:65], v[104:105], v[68:69]
	v_pk_mul_f32 v[66:67], v[98:99], v[44:45]
	v_pk_mul_f32 v[70:71], v[100:101], v[46:47]
	v_mul_f32_e32 v45, v53, v53
	v_mul_f32_e32 v47, v55, v55
	v_mul_f32_e32 v61, v49, v49
	v_mul_f32_e32 v69, v51, v51
	global_store_dwordx4 v57, v[40:43], s[14:15]
	v_fmac_f32_e32 v72, v68, v68
	v_fmac_f32_e32 v73, v60, v60
	v_fmac_f32_e32 v78, v46, v46
	v_fmac_f32_e32 v79, v44, v44
	v_cvt_pk_bf16_f32 v40, v64, v65
	v_fmac_f32_e32 v45, v52, v52
	v_fmac_f32_e32 v47, v54, v54
	v_fmac_f32_e32 v61, v48, v48
	v_fmac_f32_e32 v69, v50, v50
	v_cvt_pk_bf16_f32 v41, v62, v63
	v_cvt_pk_bf16_f32 v42, v70, v71
	v_cvt_pk_bf16_f32 v43, v66, v67
	v_add_f32_e32 v44, v72, v73
	v_add_f32_e32 v46, v78, v79
	global_store_dwordx4 v57, v[40:43], s[86:87]
	v_add_f32_e32 v45, v45, v47
	v_add_f32_e32 v47, v61, v69
	v_cvt_pk_bf16_f32 v40, v52, v53
	v_cvt_pk_bf16_f32 v41, v54, v55
	v_cvt_pk_bf16_f32 v42, v48, v49
	v_cvt_pk_bf16_f32 v43, v50, v51
	v_add_f32_e32 v44, v44, v46
	global_store_dwordx4 v59, v[40:43], s[14:15]
	v_pk_mul_f32 v[48:49], v[76:77], v[48:49]
	s_nop 0
	v_add_f32_e32 v40, v45, v47
	v_add_f32_e32 v43, v44, v40
	v_pk_mul_f32 v[44:45], v[80:81], v[54:55]
	ds_bpermute_b32 v54, v168, v43
	v_pk_mul_f32 v[40:41], v[82:83], v[52:53]
	v_pk_mul_f32 v[46:47], v[74:75], v[50:51]
	v_cvt_pk_bf16_f32 v42, v40, v41
	s_waitcnt lgkmcnt(0)
	v_add_f32_e32 v40, v43, v54
	ds_bpermute_b32 v41, v169, v40
	v_cvt_pk_bf16_f32 v43, v44, v45
	v_cvt_pk_bf16_f32 v44, v48, v49
	v_cvt_pk_bf16_f32 v45, v46, v47
	global_store_dwordx4 v59, v[42:45], s[86:87]
	s_and_saveexec_b64 s[24:25], s[0:1]
	s_cbranch_execz .LBB0_902
	v_add_u32_e32 v42, 0xa0, v56
	v_mov_b32_e32 v43, v137
	v_lshl_add_u64 v[42:43], v[42:43], 2, s[12:13]
	s_waitcnt lgkmcnt(0)
	v_add_f32_e32 v40, v40, v41
	global_atomic_add_f32 v[42:43], v40, off
.LBB0_902:
	s_or_b64 exec, exec, s[24:25]
	s_nop 0
	v_lshlrev_b32_e32 v44, 16, v20
	v_and_b32_e32 v45, 0xffff0000, v20
	v_lshlrev_b32_e32 v20, 16, v21
	v_and_b32_e32 v21, 0xffff0000, v21
	v_lshlrev_b32_e32 v46, 16, v22
	v_and_b32_e32 v47, 0xffff0000, v22
	v_lshlrev_b32_e32 v22, 16, v23
	v_and_b32_e32 v23, 0xffff0000, v23
	s_waitcnt lgkmcnt(0)
	v_lshl_add_u64 v[40:41], s[14:15], 0, v[136:137]
	v_pk_fma_f32 v[14:15], v[38:39], v[14:15], v[20:21]
	v_pk_fma_f32 v[12:13], v[36:37], v[12:13], v[44:45]
	v_pk_fma_f32 v[20:21], v[34:35], v[10:11], v[22:23]
	v_pk_fma_f32 v[22:23], v[32:33], v[8:9], v[46:47]
	v_cvt_pk_bf16_f32 v8, v12, v13
	v_cvt_pk_bf16_f32 v9, v14, v15
	v_mov_b32_e32 v59, v137
	v_cvt_pk_bf16_f32 v10, v22, v23
	v_cvt_pk_bf16_f32 v11, v20, v21
	global_store_dwordx4 v[40:41], v[8:11], off
	v_lshl_add_u64 v[42:43], s[14:15], 0, v[58:59]
	s_nop 0
	v_mul_f32_e32 v8, v13, v13
	v_mul_f32_e32 v9, v15, v15
	v_fmac_f32_e32 v8, v12, v12
	v_fmac_f32_e32 v9, v14, v14
	v_add_f32_e32 v8, v8, v9
	v_mul_f32_e32 v9, v23, v23
	v_mul_f32_e32 v10, v21, v21
	v_fmac_f32_e32 v9, v22, v22
	v_fmac_f32_e32 v10, v20, v20
	v_add_f32_e32 v9, v9, v10
	v_add_f32_e32 v32, v8, v9
	v_pk_mul_f32 v[10:11], v[102:103], v[14:15]
	v_pk_mul_f32 v[8:9], v[104:105], v[12:13]
	v_pk_mul_f32 v[12:13], v[98:99], v[20:21]
	v_pk_mul_f32 v[14:15], v[100:101], v[22:23]
	v_cvt_pk_bf16_f32 v8, v8, v9
	v_cvt_pk_bf16_f32 v9, v10, v11
	s_nop 0
	v_cvt_pk_bf16_f32 v10, v14, v15
	v_cvt_pk_bf16_f32 v11, v12, v13
	v_lshl_add_u64 v[12:13], s[86:87], 0, v[136:137]
	global_store_dwordx4 v[12:13], v[8:11], off
	s_nop 0
	v_lshlrev_b32_e32 v12, 16, v18
	v_and_b32_e32 v13, 0xffff0000, v18
	v_lshlrev_b32_e32 v8, 16, v16
	v_and_b32_e32 v9, 0xffff0000, v16
	v_lshlrev_b32_e32 v10, 16, v17
	v_and_b32_e32 v11, 0xffff0000, v17
	v_lshlrev_b32_e32 v14, 16, v19
	v_and_b32_e32 v15, 0xffff0000, v19
	v_pk_fma_f32 v[6:7], v[30:31], v[6:7], v[10:11]
	v_pk_fma_f32 v[4:5], v[28:29], v[4:5], v[8:9]
	v_pk_fma_f32 v[10:11], v[24:25], v[0:1], v[12:13]
	v_cvt_pk_bf16_f32 v0, v4, v5
	v_cvt_pk_bf16_f32 v1, v6, v7
	v_pk_fma_f32 v[8:9], v[26:27], v[2:3], v[14:15]
	v_cvt_pk_bf16_f32 v2, v10, v11
	s_nop 0
	v_cvt_pk_bf16_f32 v3, v8, v9
	global_store_dwordx4 v[42:43], v[0:3], off
	s_nop 1
	v_mul_f32_e32 v0, v5, v5
	v_mul_f32_e32 v1, v7, v7
	v_fmac_f32_e32 v0, v4, v4
	v_fmac_f32_e32 v1, v6, v6
	v_add_f32_e32 v0, v0, v1
	v_mul_f32_e32 v1, v11, v11
	v_mul_f32_e32 v2, v9, v9
	v_fmac_f32_e32 v1, v10, v10
	v_fmac_f32_e32 v2, v8, v8
	v_add_f32_e32 v1, v1, v2
	v_add_f32_e32 v0, v0, v1
	v_add_f32_e32 v12, v32, v0
	ds_bpermute_b32 v13, v168, v12
	v_pk_mul_f32 v[0:1], v[80:81], v[6:7]
	v_pk_mul_f32 v[2:3], v[82:83], v[4:5]
	v_pk_mul_f32 v[6:7], v[74:75], v[8:9]
	v_cvt_pk_bf16_f32 v2, v2, v3
	v_cvt_pk_bf16_f32 v3, v0, v1
	s_waitcnt lgkmcnt(0)
	v_add_f32_e32 v0, v12, v13
	ds_bpermute_b32 v1, v169, v0
	v_pk_mul_f32 v[4:5], v[76:77], v[10:11]
	s_nop 0
	v_cvt_pk_bf16_f32 v4, v4, v5
	v_cvt_pk_bf16_f32 v5, v6, v7
	v_lshl_add_u64 v[6:7], s[86:87], 0, v[58:59]
	global_store_dwordx4 v[6:7], v[2:5], off
	s_and_saveexec_b64 s[24:25], s[0:1]
	s_cbranch_execz .LBB0_904
	v_add_u32_e32 v136, 0xb0, v56
	v_lshl_add_u64 v[2:3], v[136:137], 2, s[12:13]
	s_waitcnt lgkmcnt(0)
	v_add_f32_e32 v0, v0, v1
	global_atomic_add_f32 v[2:3], v0, off

;     __device__ __forceinline__ void operator()(const f32x4 (&acc)[2][2][4][2], const Unit& u, int wr, int wc, int fr, int fq) const {
;         const int row0 = u.pm * 256 + wr * 64 + fr, col0 = u.pn * 256 + wc * 32 + 8 * fq;
;         const int mb = u.pm < 64 ? (u.pm >> 4) : 4;
;         float* SSn = (float*)(ws + WS_SS) + ss_off;
;         const float* gate = (const float*)(ws + WS_MOD) + gate_off + (size_t)mb * 9216; const float* gn = (const float*)(ws + WS_NG) + gn_off; const float* scn = (const float*)(ws + WS_MOD) + scn_off + (size_t)mb * 9216;
;         f32x4 gv[2][2], bv[2][2], wv[2][2];
; #pragma unroll
;         for (int bj = 0; bj < 2; ++bj)
; #pragma unroll
;             for (int n = 0; n < 2; ++n) { const int cc = col0 + bj * 128 + 4 * n;
;                 gv[bj][n] = *(const f32x4*)(gate + cc) * gmul;
;                 bv[bj][n] = HASBIAS ? *(const f32x4*)(bias + cc) : (f32x4){0.f, 0.f, 0.f, 0.f};
;                 wv[bj][n] = FUSE ? *(const f32x4*)(gn + cc) * (*(const f32x4*)(scn + cc) + 1.0f) : (f32x4){0.f, 0.f, 0.f, 0.f}; }
;         const unsigned e0 = (unsigned)(row0 * D + col0);
;         const char* bsc = (const char*)base0; char* Hc = (char*)(ws + WS_H); char* HBc = (char*)(ws + WS_XN);
;         constexpr int RGB = 2;
; #pragma unroll
;         for (int rg = 0; rg < 8 / RGB; ++rg) {
;             u32x4 braw[INPLACE ? RGB : 1][2]; f32x4 bb[INPLACE ? 1 : RGB][2][2];
; #pragma unroll
;             for (int mm = 0; mm < RGB; ++mm) { const int q = rg * RGB + mm, ai = q >> 2, m = q & 3;
; #pragma unroll
;                 for (int bj = 0; bj < 2; ++bj) { const unsigned e = e0 + (unsigned)((ai * 128 + m * 16) * D + bj * 128);
;                     if constexpr (INPLACE) braw[mm][bj] = *(const u32x4*)(Hc + (size_t)(e * 2u));
;                     else { bb[mm][bj][0] = *(const f32x4*)(bsc + (size_t)(e * 4u)); bb[mm][bj][1] = *(const f32x4*)(bsc + (size_t)(e * 4u + 16u)); } } }
; #pragma unroll
;             for (int mm = 0; mm < RGB; ++mm) { const int q = rg * RGB + mm, ai = q >> 2, m = q & 3; float ssum = 0.f;
; #pragma unroll
;                 for (int bj = 0; bj < 2; ++bj) { const unsigned e = e0 + (unsigned)((ai * 128 + m * 16) * D + bj * 128);
;                     f32x4 r0, r1;
;                     if constexpr (INPLACE) { const u32x4 q4 = braw[mm][bj];
.LBB0_1053:
	s_ashr_i32 s24, s52, 4
	v_lshl_or_b32 v0, s53, 8, v192
	s_mul_i32 s27, s24, 0x9000
	s_mul_hi_i32 s26, s24, 0x9000
	s_add_u32 s24, s45, s27
	s_waitcnt lgkmcnt(0)
	v_ashrrev_i32_e32 v1, 31, v0
	v_lshl_add_u32 v24, s52, 8, v179
	s_addc_u32 s25, s46, s26
	v_lshlrev_b64 v[2:3], 2, v[0:1]
	v_lshlrev_b32_e32 v1, 11, v24
	v_lshl_add_u64 v[4:5], s[24:25], 0, v[2:3]
	v_lshl_add_u32 v196, v0, 1, v1
	global_load_dwordx4 v[60:63], v[4:5], off
	global_load_dwordx4 v[64:67], v[4:5], off offset:16
	global_load_dwordx4 v[70:73], v[4:5], off offset:512
	global_load_dwordx4 v[98:101], v[4:5], off offset:528
	global_load_dwordx4 v[102:105], v196, s[16:17]
	s_add_u32 s24, s47, s27
	s_addc_u32 s25, s48, s26
	v_lshl_add_u64 v[4:5], s[24:25], 0, v[2:3]
	global_load_dwordx4 v[198:201], v[4:5], off
	global_load_dwordx4 v[202:205], v[4:5], off offset:16
	global_load_dwordx4 v[206:209], v[4:5], off offset:512
	global_load_dwordx4 v[210:213], v[4:5], off offset:528
	v_lshl_add_u64 v[2:3], s[12:13], 0, v[2:3]
	global_load_dwordx4 v[214:217], v[2:3], off offset:16
	global_load_dwordx4 v[218:221], v[2:3], off
	v_or_b32_e32 v0, 0x80, v0
	v_ashrrev_i32_e32 v1, 31, v0
	v_lshl_add_u64 v[0:1], v[0:1], 2, s[12:13]
	v_or_b32_e32 v25, 0x100, v196
	global_load_dwordx4 v[222:225], v[0:1], off
	global_load_dwordx4 v[226:229], v[0:1], off offset:16
	global_load_dwordx4 v[230:233], v25, s[16:17]
	v_add_u32_e32 v136, 0x8000, v196
	v_add_u32_e32 v190, 0x8100, v196
	global_load_dwordx4 v[4:7], v136, s[16:17]
	global_load_dwordx4 v[0:3], v190, s[16:17]
	s_waitcnt vmcnt(0)
	v_add_u32_e32 v252, 0x10000, v196
	global_load_dwordx4 v[238:241], v252, s[16:17]
	global_load_dwordx4 v[242:245], v252, s[16:17] offset:256
	v_add_u32_e32 v252, 0x18000, v196
	global_load_dwordx4 v[246:249], v252, s[16:17]
	global_load_dwordx2 v[250:251], v252, s[16:17] offset:256
	global_load_dwordx2 v[254:255], v252, s[16:17] offset:264
	v_pk_mul_f32 v[94:95], v[62:63], 0.5 op_sel_hi:[1,0]
	v_pk_mul_f32 v[86:87], v[60:61], 0.5 op_sel_hi:[1,0]
	v_pk_mul_f32 v[84:85], v[66:67], 0.5 op_sel_hi:[1,0]
	v_pk_mul_f32 v[82:83], v[64:65], 0.5 op_sel_hi:[1,0]
	v_pk_mul_f32 v[68:69], v[72:73], 0.5 op_sel_hi:[1,0]
	v_pk_mul_f32 v[66:67], v[70:71], 0.5 op_sel_hi:[1,0]
	v_lshlrev_b32_e32 v62, 16, v102
	v_and_b32_e32 v63, 0xffff0000, v102
	v_lshlrev_b32_e32 v64, 16, v103
	v_and_b32_e32 v65, 0xffff0000, v103
	v_lshlrev_b32_e32 v70, 16, v104
	v_and_b32_e32 v71, 0xffff0000, v104
	v_lshlrev_b32_e32 v72, 16, v105
	v_and_b32_e32 v73, 0xffff0000, v105
	v_pk_fma_f32 v[234:235], v[184:185], v[94:95], v[64:65]
	v_pk_fma_f32 v[188:189], v[188:189], v[86:87], v[62:63]
	v_pk_fma_f32 v[186:187], v[186:187], v[84:85], v[72:73]
	v_pk_fma_f32 v[236:237], v[182:183], v[82:83], v[70:71]
	v_pk_add_f32 v[62:63], v[200:201], 1.0 op_sel_hi:[1,0]
	v_pk_add_f32 v[200:201], v[206:207], 1.0 op_sel_hi:[1,0]
	v_mul_f32_e32 v191, v189, v189
	v_mul_f32_e32 v197, v235, v235
	v_mul_f32_e32 v206, v237, v237
	v_mul_f32_e32 v207, v187, v187
	v_pk_add_f32 v[64:65], v[198:199], 1.0 op_sel_hi:[1,0]
	v_cvt_pk_bf16_f32 v182, v188, v189
	v_cvt_pk_bf16_f32 v183, v234, v235
	v_fmac_f32_e32 v191, v188, v188
	v_fmac_f32_e32 v197, v234, v234
	v_fmac_f32_e32 v206, v236, v236
	v_fmac_f32_e32 v207, v186, v186
	v_pk_add_f32 v[70:71], v[204:205], 1.0 op_sel_hi:[1,0]
	v_pk_add_f32 v[72:73], v[202:203], 1.0 op_sel_hi:[1,0]
	v_cvt_pk_bf16_f32 v184, v236, v237
	v_cvt_pk_bf16_f32 v185, v186, v187
	v_pk_mul_f32 v[102:103], v[220:221], v[62:63]
	v_pk_mul_f32 v[104:105], v[218:219], v[64:65]
	global_store_dwordx4 v196, v[182:185], s[16:17]
	v_pk_mul_f32 v[60:61], v[100:101], 0.5 op_sel_hi:[1,0]
	v_pk_mul_f32 v[26:27], v[98:99], 0.5 op_sel_hi:[1,0]
	v_add_f32_e32 v182, v191, v197
	v_add_f32_e32 v183, v206, v207
	v_pk_mul_f32 v[98:99], v[216:217], v[70:71]
	v_pk_mul_f32 v[100:101], v[214:215], v[72:73]
	v_pk_mul_f32 v[184:185], v[102:103], v[234:235]
	v_add_f32_e32 v191, v182, v183
	v_pk_mul_f32 v[182:183], v[104:105], v[188:189]
	v_pk_mul_f32 v[186:187], v[98:99], v[186:187]
	v_pk_mul_f32 v[188:189], v[100:101], v[236:237]
	v_cvt_pk_bf16_f32 v182, v182, v183
	v_cvt_pk_bf16_f32 v183, v184, v185
	v_pk_mul_f32 v[72:73], v[222:223], v[200:201]
	v_cvt_pk_bf16_f32 v184, v188, v189
	v_cvt_pk_bf16_f32 v185, v186, v187
	global_store_dwordx4 v196, v[182:185], s[86:87]
	v_lshlrev_b32_e32 v186, 16, v232
	v_and_b32_e32 v187, 0xffff0000, v232
	v_lshlrev_b32_e32 v182, 16, v230
	v_and_b32_e32 v183, 0xffff0000, v230
	v_lshlrev_b32_e32 v184, 16, v231
	v_and_b32_e32 v185, 0xffff0000, v231
	v_lshlrev_b32_e32 v188, 16, v233
	v_and_b32_e32 v189, 0xffff0000, v233
	v_pk_fma_f32 v[174:175], v[174:175], v[68:69], v[184:185]
	v_pk_fma_f32 v[172:173], v[172:173], v[66:67], v[182:183]
	v_pk_fma_f32 v[184:185], v[168:169], v[26:27], v[186:187]
	v_cvt_pk_bf16_f32 v168, v172, v173
	v_cvt_pk_bf16_f32 v169, v174, v175
	v_pk_fma_f32 v[182:183], v[170:171], v[60:61], v[188:189]
	v_cvt_pk_bf16_f32 v170, v184, v185
	v_pk_add_f32 v[198:199], v[208:209], 1.0 op_sel_hi:[1,0]
	v_cvt_pk_bf16_f32 v171, v182, v183
	global_store_dwordx4 v25, v[168:171], s[16:17]
	v_pk_add_f32 v[202:203], v[212:213], 1.0 op_sel_hi:[1,0]
	v_pk_add_f32 v[204:205], v[210:211], 1.0 op_sel_hi:[1,0]
	v_mul_f32_e32 v168, v173, v173
	v_mul_f32_e32 v169, v175, v175
	v_fmac_f32_e32 v168, v172, v172
	v_fmac_f32_e32 v169, v174, v174
	v_add_f32_e32 v168, v168, v169
	v_mul_f32_e32 v169, v185, v185
	v_mul_f32_e32 v170, v183, v183
	v_fmac_f32_e32 v169, v184, v184
	v_fmac_f32_e32 v170, v182, v182
	v_add_f32_e32 v169, v169, v170
	v_add_f32_e32 v168, v168, v169
	v_and_b32_e32 v170, 64, v177
	v_add_f32_e32 v169, v191, v168
	v_xor_b32_e32 v168, 16, v177
	v_add_u32_e32 v186, 64, v170
	v_cmp_lt_i32_e32 vcc, v168, v186
	v_pk_mul_f32 v[170:171], v[72:73], v[172:173]
	v_pk_mul_f32 v[70:71], v[224:225], v[198:199]
	v_cndmask_b32_e32 v168, v177, v168, vcc
	v_lshlrev_b32_e32 v168, 2, v168
	ds_bpermute_b32 v187, v168, v169
	v_cvt_pk_bf16_f32 v172, v170, v171
	v_pk_mul_f32 v[62:63], v[228:229], v[202:203]
	v_pk_mul_f32 v[64:65], v[226:227], v[204:205]
	v_pk_mul_f32 v[174:175], v[70:71], v[174:175]
	s_waitcnt lgkmcnt(0)
	v_add_f32_e32 v170, v169, v187
	v_xor_b32_e32 v169, 32, v177
	v_cmp_lt_i32_e32 vcc, v169, v186
	v_pk_mul_f32 v[182:183], v[62:63], v[182:183]
	v_pk_mul_f32 v[184:185], v[64:65], v[184:185]
	v_cndmask_b32_e32 v169, v177, v169, vcc
	v_lshlrev_b32_e32 v169, 2, v169
	ds_bpermute_b32 v171, v169, v170
	v_cvt_pk_bf16_f32 v173, v174, v175
	v_cvt_pk_bf16_f32 v174, v184, v185
	v_cvt_pk_bf16_f32 v175, v182, v183
	global_store_dwordx4 v25, v[172:175], s[86:87]
	s_and_saveexec_b64 s[24:25], s[0:1]
	s_cbranch_execz .LBB0_1055
	v_mov_b32_e32 v25, v137
	v_lshl_add_u64 v[172:173], v[24:25], 2, s[14:15]
	s_waitcnt lgkmcnt(0)
	v_add_f32_e32 v25, v170, v171
	global_atomic_add_f32 v[172:173], v25, off

;     __device__ __forceinline__ void operator()(const f32x4 (&acc)[2][2][4][2], const Unit& u, int wr, int wc, int fr, int fq) const {
;     ...
;         for (int rg = 0; rg < 8 / RGB; ++rg) {
;             u32x4 braw[INPLACE ? RGB : 1][2]; f32x4 bb[INPLACE ? 1 : RGB][2][2];
; #pragma unroll
;             for (int mm = 0; mm < RGB; ++mm) { const int q = rg * RGB + mm, ai = q >> 2, m = q & 3;
; #pragma unroll
;                 for (int bj = 0; bj < 2; ++bj) { const unsigned e = e0 + (unsigned)((ai * 128 + m * 16) * D + bj * 128);
;                     if constexpr (INPLACE) braw[mm][bj] = *(const u32x4*)(Hc + (size_t)(e * 2u));
;                     else { bb[mm][bj][0] = *(const f32x4*)(bsc + (size_t)(e * 4u)); bb[mm][bj][1] = *(const f32x4*)(bsc + (size_t)(e * 4u + 16u)); } } }
; #pragma unroll
;             for (int mm = 0; mm < RGB; ++mm) { const int q = rg * RGB + mm, ai = q >> 2, m = q & 3; float ssum = 0.f;
; #pragma unroll
;                 for (int bj = 0; bj < 2; ++bj) { const unsigned e = e0 + (unsigned)((ai * 128 + m * 16) * D + bj * 128);
;                     f32x4 r0, r1;
;                     if constexpr (INPLACE) { const u32x4 q4 = braw[mm][bj];
;                         r0 = (f32x4){__uint_as_float(q4[0] << 16), __uint_as_float(q4[0] & 0xffff0000u), __uint_as_float(q4[1] << 16), __uint_as_float(q4[1] & 0xffff0000u)};
;                         r1 = (f32x4){__uint_as_float(q4[2] << 16), __uint_as_float(q4[2] & 0xffff0000u), __uint_as_float(q4[3] << 16), __uint_as_float(q4[3] & 0xffff0000u)}; }
;                     else { r0 = bb[mm][bj][0]; r1 = bb[mm][bj][1]; }
;                     const f32x4 h0 = r0 + gv[bj][0] * (acc[ai][bj][m][0] + bv[bj][0]), h1 = r1 + gv[bj][1] * (acc[ai][bj][m][1] + bv[bj][1]);
;                     { u32x4 w; w.x = cvt_pk_bf16(h0[0], h0[1]); w.y = cvt_pk_bf16(h0[2], h0[3]); w.z = cvt_pk_bf16(h1[0], h1[1]); w.w = cvt_pk_bf16(h1[2], h1[3]); ST16(1, Hc + (size_t)(e * 2u), w); }
;                     if (FUSE) { ssum += ((h0[0] * h0[0] + h0[1] * h0[1]) + (h0[2] * h0[2] + h0[3] * h0[3])) + ((h1[0] * h1[0] + h1[1] * h1[1]) + (h1[2] * h1[2] + h1[3] * h1[3]));
;                         const f32x4 z0 = h0 * wv[bj][0], z1 = h1 * wv[bj][1];
;                         u32x4 w; w.x = cvt_pk_bf16(z0[0], z0[1]); w.y = cvt_pk_bf16(z0[2], z0[3]); w.z = cvt_pk_bf16(z1[0], z1[1]); w.w = cvt_pk_bf16(z1[2], z1[3]);
.LBB0_1057:
	s_or_b64 exec, exec, s[24:25]
	v_add_u32_e32 v25, 0x10000, v196
	v_add_u32_e32 v153, 0x10100, v196
	v_add_u32_e32 v136, 0x18000, v196
	v_add_u32_e32 v152, 0x18100, v196
	s_waitcnt lgkmcnt(0)
	s_waitcnt vmcnt(8)
	v_mov_b64_e32 v[154:155], v[238:239]
	v_mov_b64_e32 v[156:157], v[240:241]
	v_mov_b64_e32 v[158:159], v[242:243]
	v_mov_b64_e32 v[160:161], v[244:245]
	v_mov_b64_e32 v[4:5], v[246:247]
	v_mov_b64_e32 v[6:7], v[248:249]
	v_mov_b64_e32 v[0:1], v[250:251]
	v_mov_b64_e32 v[2:3], v[254:255]
	v_add_u32_e32 v252, 0x40000, v196
	global_load_dwordx4 v[238:241], v252, s[16:17]
	global_load_dwordx4 v[242:245], v252, s[16:17] offset:256
	v_add_u32_e32 v252, 0x48000, v196
	global_load_dwordx4 v[246:249], v252, s[16:17]
	global_load_dwordx2 v[250:251], v252, s[16:17] offset:256
	global_load_dwordx2 v[254:255], v252, s[16:17] offset:264
	s_nop 0
	v_lshlrev_b32_e32 v162, 16, v154
	v_and_b32_e32 v163, 0xffff0000, v154
	v_lshlrev_b32_e32 v154, 16, v155
	v_and_b32_e32 v155, 0xffff0000, v155
	v_lshlrev_b32_e32 v164, 16, v156
	v_and_b32_e32 v165, 0xffff0000, v156
	v_lshlrev_b32_e32 v156, 16, v157
	v_and_b32_e32 v157, 0xffff0000, v157
	s_nop 0
	v_lshlrev_b32_e32 v166, 16, v158
	v_and_b32_e32 v167, 0xffff0000, v158
	v_lshlrev_b32_e32 v158, 16, v159
	v_and_b32_e32 v159, 0xffff0000, v159
	v_lshlrev_b32_e32 v170, 16, v160
	v_and_b32_e32 v171, 0xffff0000, v160
	v_lshlrev_b32_e32 v160, 16, v161
	v_and_b32_e32 v161, 0xffff0000, v161
	v_pk_fma_f32 v[154:155], v[122:123], v[94:95], v[154:155]
	v_pk_fma_f32 v[162:163], v[124:125], v[86:87], v[162:163]
	v_pk_fma_f32 v[126:127], v[126:127], v[84:85], v[156:157]
	v_pk_fma_f32 v[142:143], v[142:143], v[82:83], v[164:165]
	v_pk_fma_f32 v[150:151], v[150:151], v[68:69], v[158:159]
	v_pk_fma_f32 v[148:149], v[148:149], v[66:67], v[166:167]
	v_pk_fma_f32 v[146:147], v[146:147], v[60:61], v[160:161]
	v_pk_fma_f32 v[144:145], v[144:145], v[26:27], v[170:171]
	v_cvt_pk_bf16_f32 v122, v162, v163
	v_cvt_pk_bf16_f32 v123, v154, v155
	v_cvt_pk_bf16_f32 v124, v142, v143
	v_cvt_pk_bf16_f32 v125, v126, v127
	v_mul_f32_e32 v166, v163, v163
	v_mul_f32_e32 v167, v155, v155
	v_mul_f32_e32 v170, v143, v143
	v_mul_f32_e32 v171, v127, v127
	v_pk_mul_f32 v[156:157], v[102:103], v[154:155]
	v_pk_mul_f32 v[158:159], v[104:105], v[162:163]
	v_pk_mul_f32 v[160:161], v[98:99], v[126:127]
	v_pk_mul_f32 v[164:165], v[100:101], v[142:143]
	v_mul_f32_e32 v127, v149, v149
	v_mul_f32_e32 v143, v151, v151
	v_mul_f32_e32 v155, v145, v145
	v_mul_f32_e32 v163, v147, v147
	v_fmac_f32_e32 v166, v162, v162
	v_fmac_f32_e32 v167, v154, v154
	v_fmac_f32_e32 v170, v142, v142
	v_fmac_f32_e32 v171, v126, v126
	v_fmac_f32_e32 v127, v148, v148
	v_fmac_f32_e32 v143, v150, v150
	v_fmac_f32_e32 v155, v144, v144
	v_fmac_f32_e32 v163, v146, v146
	global_store_dwordx4 v25, v[122:125], s[16:17]
	v_add_f32_e32 v126, v166, v167
	v_add_f32_e32 v142, v170, v171
	v_cvt_pk_bf16_f32 v122, v158, v159
	v_cvt_pk_bf16_f32 v123, v156, v157
	v_cvt_pk_bf16_f32 v124, v164, v165
	v_cvt_pk_bf16_f32 v125, v160, v161
	global_store_dwordx4 v25, v[122:125], s[86:87]
	v_add_f32_e32 v25, v127, v143
	v_add_f32_e32 v127, v155, v163
	v_add_f32_e32 v126, v126, v142
	v_add_f32_e32 v25, v25, v127
	v_cvt_pk_bf16_f32 v122, v148, v149
	v_cvt_pk_bf16_f32 v123, v150, v151
	v_cvt_pk_bf16_f32 v124, v144, v145
	v_cvt_pk_bf16_f32 v125, v146, v147
	v_add_f32_e32 v25, v126, v25
	global_store_dwordx4 v153, v[122:125], s[16:17]
	ds_bpermute_b32 v125, v168, v25
	v_pk_mul_f32 v[126:127], v[70:71], v[150:151]
	v_pk_mul_f32 v[122:123], v[72:73], v[148:149]
	v_pk_mul_f32 v[142:143], v[62:63], v[146:147]
	v_cvt_pk_bf16_f32 v124, v122, v123
	s_waitcnt lgkmcnt(0)
	v_add_f32_e32 v25, v25, v125
	ds_bpermute_b32 v122, v169, v25
	v_pk_mul_f32 v[144:145], v[64:65], v[144:145]
	v_cvt_pk_bf16_f32 v125, v126, v127
	s_nop 0
	v_cvt_pk_bf16_f32 v126, v144, v145
	v_cvt_pk_bf16_f32 v127, v142, v143
	global_store_dwordx4 v153, v[124:127], s[86:87]
	s_and_saveexec_b64 s[24:25], s[0:1]
	s_cbranch_execz .LBB0_1059
	v_or_b32_e32 v124, 32, v24
	v_mov_b32_e32 v125, v137
	v_lshl_add_u64 v[124:125], v[124:125], 2, s[14:15]
	s_waitcnt lgkmcnt(0)
	v_add_f32_e32 v25, v25, v122
	global_atomic_add_f32 v[124:125], v25, off
.LBB0_1059:
	s_or_b64 exec, exec, s[24:25]
	s_nop 0
	v_lshlrev_b32_e32 v126, 16, v4
	v_and_b32_e32 v127, 0xffff0000, v4
	v_lshlrev_b32_e32 v4, 16, v5
	v_and_b32_e32 v5, 0xffff0000, v5
	s_waitcnt lgkmcnt(0)
;     __device__ __forceinline__ void operator()(const f32x4 (&acc)[2][2][4][2], const Unit& u, int wr, int wc, int fr, int fq) const {
;     ...
;         for (int rg = 0; rg < 8 / RGB; ++rg) {
;             u32x4 braw[INPLACE ? RGB : 1][2]; f32x4 bb[INPLACE ? 1 : RGB][2][2];
; #pragma unroll
;             for (int mm = 0; mm < RGB; ++mm) { const int q = rg * RGB + mm, ai = q >> 2, m = q & 3;
; #pragma unroll
;                 for (int bj = 0; bj < 2; ++bj) { const unsigned e = e0 + (unsigned)((ai * 128 + m * 16) * D + bj * 128);
;                     if constexpr (INPLACE) braw[mm][bj] = *(const u32x4*)(Hc + (size_t)(e * 2u));
;                     else { bb[mm][bj][0] = *(const f32x4*)(bsc + (size_t)(e * 4u)); bb[mm][bj][1] = *(const f32x4*)(bsc + (size_t)(e * 4u + 16u)); } } }
; #pragma unroll
;             for (int mm = 0; mm < RGB; ++mm) { const int q = rg * RGB + mm, ai = q >> 2, m = q & 3; float ssum = 0.f;
; #pragma unroll
;                 for (int bj = 0; bj < 2; ++bj) { const unsigned e = e0 + (unsigned)((ai * 128 + m * 16) * D + bj * 128);
;                     f32x4 r0, r1;
;                     if constexpr (INPLACE) { const u32x4 q4 = braw[mm][bj];
;                         r0 = (f32x4){__uint_as_float(q4[0] << 16), __uint_as_float(q4[0] & 0xffff0000u), __uint_as_float(q4[1] << 16), __uint_as_float(q4[1] & 0xffff0000u)};
;                         r1 = (f32x4){__uint_as_float(q4[2] << 16), __uint_as_float(q4[2] & 0xffff0000u), __uint_as_float(q4[3] << 16), __uint_as_float(q4[3] & 0xffff0000u)}; }
;                     else { r0 = bb[mm][bj][0]; r1 = bb[mm][bj][1]; }
;                     const f32x4 h0 = r0 + gv[bj][0] * (acc[ai][bj][m][0] + bv[bj][0]), h1 = r1 + gv[bj][1] * (acc[ai][bj][m][1] + bv[bj][1]);
;                     { u32x4 w; w.x = cvt_pk_bf16(h0[0], h0[1]); w.y = cvt_pk_bf16(h0[2], h0[3]); w.z = cvt_pk_bf16(h1[0], h1[1]); w.w = cvt_pk_bf16(h1[2], h1[3]); ST16(1, Hc + (size_t)(e * 2u), w); }
;                     if (FUSE) { ssum += ((h0[0] * h0[0] + h0[1] * h0[1]) + (h0[2] * h0[2] + h0[3] * h0[3])) + ((h1[0] * h1[0] + h1[1] * h1[1]) + (h1[2] * h1[2] + h1[3] * h1[3]));
;                         const f32x4 z0 = h0 * wv[bj][0], z1 = h1 * wv[bj][1];
;                         u32x4 w; w.x = cvt_pk_bf16(z0[0], z0[1]); w.y = cvt_pk_bf16(z0[2], z0[3]); w.z = cvt_pk_bf16(z1[0], z1[1]); w.w = cvt_pk_bf16(z1[2], z1[3]);
	v_lshl_add_u64 v[122:123], s[16:17], 0, v[136:137]
	v_lshlrev_b32_e32 v142, 16, v6
	v_and_b32_e32 v143, 0xffff0000, v6
	v_lshlrev_b32_e32 v6, 16, v7
	v_and_b32_e32 v7, 0xffff0000, v7
	v_pk_fma_f32 v[120:121], v[120:121], v[94:95], v[4:5]
	v_pk_fma_f32 v[118:119], v[118:119], v[86:87], v[126:127]
	v_pk_fma_f32 v[116:117], v[116:117], v[84:85], v[6:7]
	v_cvt_pk_bf16_f32 v4, v118, v119
	v_cvt_pk_bf16_f32 v5, v120, v121
	v_pk_fma_f32 v[114:115], v[114:115], v[82:83], v[142:143]
	v_mov_b32_e32 v153, v137
	v_cvt_pk_bf16_f32 v6, v114, v115
	v_cvt_pk_bf16_f32 v7, v116, v117
	global_store_dwordx4 v[122:123], v[4:7], off
	v_lshl_add_u64 v[124:125], s[16:17], 0, v[152:153]
	s_nop 0
	v_mul_f32_e32 v4, v119, v119
	v_mul_f32_e32 v5, v121, v121
	v_fmac_f32_e32 v4, v118, v118
	v_fmac_f32_e32 v5, v120, v120
	v_add_f32_e32 v4, v4, v5
	v_mul_f32_e32 v5, v115, v115
	v_mul_f32_e32 v6, v117, v117
	v_fmac_f32_e32 v5, v114, v114
	v_fmac_f32_e32 v6, v116, v116
	v_add_f32_e32 v5, v5, v6
	v_add_f32_e32 v25, v4, v5
	v_pk_mul_f32 v[6:7], v[102:103], v[120:121]
	v_pk_mul_f32 v[4:5], v[104:105], v[118:119]
	v_pk_mul_f32 v[114:115], v[100:101], v[114:115]
	v_cvt_pk_bf16_f32 v4, v4, v5
	v_cvt_pk_bf16_f32 v5, v6, v7
	v_pk_mul_f32 v[116:117], v[98:99], v[116:117]
	v_cvt_pk_bf16_f32 v6, v114, v115
	v_lshl_add_u64 v[114:115], s[86:87], 0, v[136:137]
	v_cvt_pk_bf16_f32 v7, v116, v117
	global_store_dwordx4 v[114:115], v[4:7], off
	s_nop 0
	s_nop 0
	v_lshlrev_b32_e32 v4, 16, v0
	v_and_b32_e32 v5, 0xffff0000, v0
	v_lshlrev_b32_e32 v0, 16, v1
	v_and_b32_e32 v1, 0xffff0000, v1
	v_lshlrev_b32_e32 v6, 16, v2
	v_and_b32_e32 v7, 0xffff0000, v2
	v_lshlrev_b32_e32 v2, 16, v3
	v_and_b32_e32 v3, 0xffff0000, v3
	v_pk_fma_f32 v[112:113], v[112:113], v[68:69], v[0:1]
	v_pk_fma_f32 v[4:5], v[110:111], v[66:67], v[4:5]
	v_pk_fma_f32 v[108:109], v[108:109], v[60:61], v[2:3]
	v_cvt_pk_bf16_f32 v0, v4, v5
	v_cvt_pk_bf16_f32 v1, v112, v113
	v_pk_fma_f32 v[6:7], v[106:107], v[26:27], v[6:7]
	v_pk_mul_f32 v[106:107], v[62:63], v[108:109]
	v_cvt_pk_bf16_f32 v2, v6, v7
	v_cvt_pk_bf16_f32 v3, v108, v109
	global_store_dwordx4 v[124:125], v[0:3], off
	s_nop 1
	v_mul_f32_e32 v0, v5, v5
	v_mul_f32_e32 v1, v113, v113
	v_fmac_f32_e32 v0, v4, v4
	v_fmac_f32_e32 v1, v112, v112
	v_add_f32_e32 v0, v0, v1
	v_mul_f32_e32 v1, v7, v7
	v_mul_f32_e32 v2, v109, v109
	v_fmac_f32_e32 v1, v6, v6
	v_fmac_f32_e32 v2, v108, v108
	v_add_f32_e32 v1, v1, v2
	v_add_f32_e32 v0, v0, v1
	v_add_f32_e32 v25, v25, v0
	ds_bpermute_b32 v110, v168, v25
	v_pk_mul_f32 v[0:1], v[70:71], v[112:113]
	v_pk_mul_f32 v[2:3], v[72:73], v[4:5]
	v_pk_mul_f32 v[4:5], v[64:65], v[6:7]
	v_cvt_pk_bf16_f32 v2, v2, v3
	v_cvt_pk_bf16_f32 v3, v0, v1
	s_waitcnt lgkmcnt(0)
	v_add_f32_e32 v0, v25, v110
	ds_bpermute_b32 v1, v169, v0
	v_lshl_add_u64 v[6:7], s[86:87], 0, v[152:153]
	v_cvt_pk_bf16_f32 v4, v4, v5
	v_cvt_pk_bf16_f32 v5, v106, v107
	global_store_dwordx4 v[6:7], v[2:5], off
	s_and_saveexec_b64 s[24:25], s[0:1]
	s_cbranch_execz .LBB0_1061
	v_or_b32_e32 v136, 48, v24
	v_lshl_add_u64 v[2:3], v[136:137], 2, s[14:15]
	s_waitcnt lgkmcnt(0)
	v_add_f32_e32 v0, v0, v1
	global_atomic_add_f32 v[2:3], v0, off
.LBB0_1061:
	s_or_b64 exec, exec, s[24:25]
	v_add_u32_e32 v25, 0x40000, v196
	v_add_u32_e32 v107, 0x40100, v196
	v_add_u32_e32 v136, 0x48000, v196
	v_add_u32_e32 v106, 0x48100, v196
	s_waitcnt lgkmcnt(0)
	s_waitcnt vmcnt(8)
	v_mov_b64_e32 v[108:109], v[238:239]
	v_mov_b64_e32 v[110:111], v[240:241]
	v_mov_b64_e32 v[112:113], v[242:243]
	v_mov_b64_e32 v[114:115], v[244:245]
	v_mov_b64_e32 v[4:5], v[246:247]
	v_mov_b64_e32 v[6:7], v[248:249]
	v_mov_b64_e32 v[0:1], v[250:251]
	v_mov_b64_e32 v[2:3], v[254:255]
	v_add_u32_e32 v252, 0x50000, v196
	global_load_dwordx4 v[238:241], v252, s[16:17]
	global_load_dwordx4 v[242:245], v252, s[16:17] offset:256
	v_add_u32_e32 v252, 0x58000, v196
	global_load_dwordx4 v[246:249], v252, s[16:17]
	global_load_dwordx2 v[250:251], v252, s[16:17] offset:256
	global_load_dwordx2 v[254:255], v252, s[16:17] offset:264
	s_nop 0
	v_lshlrev_b32_e32 v116, 16, v108
	v_and_b32_e32 v117, 0xffff0000, v108
	v_lshlrev_b32_e32 v108, 16, v109
	v_and_b32_e32 v109, 0xffff0000, v109
	v_lshlrev_b32_e32 v118, 16, v110
	v_and_b32_e32 v119, 0xffff0000, v110
	v_lshlrev_b32_e32 v110, 16, v111
	v_and_b32_e32 v111, 0xffff0000, v111
	s_nop 0
	v_lshlrev_b32_e32 v120, 16, v112
	v_and_b32_e32 v121, 0xffff0000, v112
	v_lshlrev_b32_e32 v112, 16, v113
	v_and_b32_e32 v113, 0xffff0000, v113
	v_lshlrev_b32_e32 v122, 16, v114
	v_and_b32_e32 v123, 0xffff0000, v114
	v_lshlrev_b32_e32 v114, 16, v115
	v_and_b32_e32 v115, 0xffff0000, v115
	v_pk_fma_f32 v[108:109], v[74:75], v[94:95], v[108:109]
	v_pk_fma_f32 v[116:117], v[76:77], v[86:87], v[116:117]
	v_pk_fma_f32 v[78:79], v[78:79], v[84:85], v[110:111]
	v_pk_fma_f32 v[80:81], v[80:81], v[82:83], v[118:119]
	v_pk_fma_f32 v[96:97], v[96:97], v[68:69], v[112:113]
	v_pk_fma_f32 v[92:93], v[92:93], v[66:67], v[120:121]
	v_pk_fma_f32 v[90:91], v[90:91], v[60:61], v[114:115]
	v_pk_fma_f32 v[88:89], v[88:89], v[26:27], v[122:123]
	v_cvt_pk_bf16_f32 v74, v116, v117
	v_cvt_pk_bf16_f32 v75, v108, v109
	v_cvt_pk_bf16_f32 v76, v80, v81
	v_cvt_pk_bf16_f32 v77, v78, v79
	v_mul_f32_e32 v120, v117, v117
	v_mul_f32_e32 v121, v109, v109
	v_mul_f32_e32 v122, v81, v81
	v_mul_f32_e32 v123, v79, v79
	v_pk_mul_f32 v[110:111], v[102:103], v[108:109]
	v_pk_mul_f32 v[112:113], v[104:105], v[116:117]
	v_pk_mul_f32 v[114:115], v[98:99], v[78:79]
	v_pk_mul_f32 v[118:119], v[100:101], v[80:81]
	v_mul_f32_e32 v79, v93, v93
	v_mul_f32_e32 v81, v97, v97
	v_mul_f32_e32 v109, v89, v89
	v_mul_f32_e32 v117, v91, v91
	v_fmac_f32_e32 v120, v116, v116
	v_fmac_f32_e32 v121, v108, v108
	v_fmac_f32_e32 v122, v80, v80
	v_fmac_f32_e32 v123, v78, v78
	v_fmac_f32_e32 v79, v92, v92
	v_fmac_f32_e32 v81, v96, v96
	v_fmac_f32_e32 v109, v88, v88
	v_fmac_f32_e32 v117, v90, v90
	global_store_dwordx4 v25, v[74:77], s[16:17]
	v_add_f32_e32 v78, v120, v121
	v_add_f32_e32 v80, v122, v123
	v_cvt_pk_bf16_f32 v74, v112, v113
	v_cvt_pk_bf16_f32 v75, v110, v111
	v_cvt_pk_bf16_f32 v76, v118, v119
	v_cvt_pk_bf16_f32 v77, v114, v115
	global_store_dwordx4 v25, v[74:77], s[86:87]
	v_add_f32_e32 v25, v79, v81
	v_add_f32_e32 v79, v109, v117
	v_add_f32_e32 v78, v78, v80
	v_add_f32_e32 v25, v25, v79
	v_cvt_pk_bf16_f32 v74, v92, v93
	v_cvt_pk_bf16_f32 v75, v96, v97
	v_cvt_pk_bf16_f32 v76, v88, v89
	v_cvt_pk_bf16_f32 v77, v90, v91
	v_add_f32_e32 v25, v78, v25
	global_store_dwordx4 v107, v[74:77], s[16:17]
	ds_bpermute_b32 v77, v168, v25
	v_pk_mul_f32 v[78:79], v[70:71], v[96:97]
	v_pk_mul_f32 v[74:75], v[72:73], v[92:93]
	v_pk_mul_f32 v[80:81], v[62:63], v[90:91]
	v_cvt_pk_bf16_f32 v76, v74, v75
	s_waitcnt lgkmcnt(0)
	v_add_f32_e32 v25, v25, v77
	ds_bpermute_b32 v74, v169, v25
	v_pk_mul_f32 v[88:89], v[64:65], v[88:89]
	v_cvt_pk_bf16_f32 v77, v78, v79
	s_nop 0
	v_cvt_pk_bf16_f32 v78, v88, v89
	v_cvt_pk_bf16_f32 v79, v80, v81
	global_store_dwordx4 v107, v[76:79], s[86:87]
	s_and_saveexec_b64 s[24:25], s[0:1]
	s_cbranch_execz .LBB0_1063
;     __device__ __forceinline__ void operator()(const f32x4 (&acc)[2][2][4][2], const Unit& u, int wr, int wc, int fr, int fq) const {
;     ...
;         for (int rg = 0; rg < 8 / RGB; ++rg) {
;             u32x4 braw[INPLACE ? RGB : 1][2]; f32x4 bb[INPLACE ? 1 : RGB][2][2];
; #pragma unroll
;             for (int mm = 0; mm < RGB; ++mm) { const int q = rg * RGB + mm, ai = q >> 2, m = q & 3;
; #pragma unroll
;                 for (int bj = 0; bj < 2; ++bj) { const unsigned e = e0 + (unsigned)((ai * 128 + m * 16) * D + bj * 128);
;                     if constexpr (INPLACE) braw[mm][bj] = *(const u32x4*)(Hc + (size_t)(e * 2u));
;                     else { bb[mm][bj][0] = *(const f32x4*)(bsc + (size_t)(e * 4u)); bb[mm][bj][1] = *(const f32x4*)(bsc + (size_t)(e * 4u + 16u)); } } }
; #pragma unroll
;             for (int mm = 0; mm < RGB; ++mm) { const int q = rg * RGB + mm, ai = q >> 2, m = q & 3; float ssum = 0.f;
; #pragma unroll
;                 for (int bj = 0; bj < 2; ++bj) { const unsigned e = e0 + (unsigned)((ai * 128 + m * 16) * D + bj * 128);
;                     f32x4 r0, r1;
;                     if constexpr (INPLACE) { const u32x4 q4 = braw[mm][bj];
;                         r0 = (f32x4){__uint_as_float(q4[0] << 16), __uint_as_float(q4[0] & 0xffff0000u), __uint_as_float(q4[1] << 16), __uint_as_float(q4[1] & 0xffff0000u)};
;                         r1 = (f32x4){__uint_as_float(q4[2] << 16), __uint_as_float(q4[2] & 0xffff0000u), __uint_as_float(q4[3] << 16), __uint_as_float(q4[3] & 0xffff0000u)}; }
;                     else { r0 = bb[mm][bj][0]; r1 = bb[mm][bj][1]; }
;                     const f32x4 h0 = r0 + gv[bj][0] * (acc[ai][bj][m][0] + bv[bj][0]), h1 = r1 + gv[bj][1] * (acc[ai][bj][m][1] + bv[bj][1]);
;                     { u32x4 w; w.x = cvt_pk_bf16(h0[0], h0[1]); w.y = cvt_pk_bf16(h0[2], h0[3]); w.z = cvt_pk_bf16(h1[0], h1[1]); w.w = cvt_pk_bf16(h1[2], h1[3]); ST16(1, Hc + (size_t)(e * 2u), w); }
;                     if (FUSE) { ssum += ((h0[0] * h0[0] + h0[1] * h0[1]) + (h0[2] * h0[2] + h0[3] * h0[3])) + ((h1[0] * h1[0] + h1[1] * h1[1]) + (h1[2] * h1[2] + h1[3] * h1[3]));
;                         const f32x4 z0 = h0 * wv[bj][0], z1 = h1 * wv[bj][1];
;                         u32x4 w; w.x = cvt_pk_bf16(z0[0], z0[1]); w.y = cvt_pk_bf16(z0[2], z0[3]); w.z = cvt_pk_bf16(z1[0], z1[1]); w.w = cvt_pk_bf16(z1[2], z1[3]);
	v_add_u32_e32 v76, 0x80, v24
	v_mov_b32_e32 v77, v137
	v_lshl_add_u64 v[76:77], v[76:77], 2, s[14:15]
	s_waitcnt lgkmcnt(0)
	v_add_f32_e32 v25, v25, v74
	global_atomic_add_f32 v[76:77], v25, off
.LBB0_1063:
	s_or_b64 exec, exec, s[24:25]
	s_nop 0
	v_lshlrev_b32_e32 v78, 16, v4
	v_and_b32_e32 v79, 0xffff0000, v4
	v_lshlrev_b32_e32 v4, 16, v5
	v_and_b32_e32 v5, 0xffff0000, v5
	s_waitcnt lgkmcnt(0)
	v_lshl_add_u64 v[74:75], s[16:17], 0, v[136:137]
	v_lshlrev_b32_e32 v80, 16, v6
	v_and_b32_e32 v81, 0xffff0000, v6
	v_lshlrev_b32_e32 v6, 16, v7
	v_and_b32_e32 v7, 0xffff0000, v7
	v_pk_fma_f32 v[58:59], v[58:59], v[94:95], v[4:5]
	v_pk_fma_f32 v[56:57], v[56:57], v[86:87], v[78:79]
	v_pk_fma_f32 v[54:55], v[54:55], v[84:85], v[6:7]
	v_cvt_pk_bf16_f32 v4, v56, v57
	v_cvt_pk_bf16_f32 v5, v58, v59
	v_pk_fma_f32 v[52:53], v[52:53], v[82:83], v[80:81]
	v_mov_b32_e32 v107, v137
	v_cvt_pk_bf16_f32 v6, v52, v53
	v_cvt_pk_bf16_f32 v7, v54, v55
	global_store_dwordx4 v[74:75], v[4:7], off
	v_lshl_add_u64 v[76:77], s[16:17], 0, v[106:107]
	s_nop 0
	v_mul_f32_e32 v4, v57, v57
	v_mul_f32_e32 v5, v59, v59
	v_fmac_f32_e32 v4, v56, v56
	v_fmac_f32_e32 v5, v58, v58
	v_add_f32_e32 v4, v4, v5
	v_mul_f32_e32 v5, v53, v53
	v_mul_f32_e32 v6, v55, v55
	v_fmac_f32_e32 v5, v52, v52
	v_fmac_f32_e32 v6, v54, v54
	v_add_f32_e32 v5, v5, v6
	v_add_f32_e32 v25, v4, v5
	v_pk_mul_f32 v[6:7], v[102:103], v[58:59]
	v_pk_mul_f32 v[4:5], v[104:105], v[56:57]
	v_pk_mul_f32 v[52:53], v[100:101], v[52:53]
	v_cvt_pk_bf16_f32 v4, v4, v5
	v_cvt_pk_bf16_f32 v5, v6, v7
	v_pk_mul_f32 v[54:55], v[98:99], v[54:55]
	v_cvt_pk_bf16_f32 v6, v52, v53
	v_lshl_add_u64 v[52:53], s[86:87], 0, v[136:137]
	v_cvt_pk_bf16_f32 v7, v54, v55
	global_store_dwordx4 v[52:53], v[4:7], off
	s_nop 0
	s_nop 0
	v_lshlrev_b32_e32 v4, 16, v0
	v_and_b32_e32 v5, 0xffff0000, v0
	v_lshlrev_b32_e32 v0, 16, v1
	v_and_b32_e32 v1, 0xffff0000, v1
	v_lshlrev_b32_e32 v6, 16, v2
	v_and_b32_e32 v7, 0xffff0000, v2
	v_lshlrev_b32_e32 v2, 16, v3
	v_and_b32_e32 v3, 0xffff0000, v3
	v_pk_fma_f32 v[50:51], v[50:51], v[68:69], v[0:1]
	v_pk_fma_f32 v[4:5], v[48:49], v[66:67], v[4:5]
	v_pk_fma_f32 v[46:47], v[46:47], v[60:61], v[2:3]
	v_cvt_pk_bf16_f32 v0, v4, v5
	v_cvt_pk_bf16_f32 v1, v50, v51
	v_pk_fma_f32 v[6:7], v[44:45], v[26:27], v[6:7]
	v_pk_mul_f32 v[44:45], v[62:63], v[46:47]
	v_cvt_pk_bf16_f32 v2, v6, v7
	v_cvt_pk_bf16_f32 v3, v46, v47
	global_store_dwordx4 v[76:77], v[0:3], off
	s_nop 1
	v_mul_f32_e32 v0, v5, v5
	v_mul_f32_e32 v1, v51, v51
	v_fmac_f32_e32 v0, v4, v4
	v_fmac_f32_e32 v1, v50, v50
	v_add_f32_e32 v0, v0, v1
	v_mul_f32_e32 v1, v7, v7
	v_mul_f32_e32 v2, v47, v47
	v_fmac_f32_e32 v1, v6, v6
	v_fmac_f32_e32 v2, v46, v46
	v_add_f32_e32 v1, v1, v2
	v_add_f32_e32 v0, v0, v1
	v_add_f32_e32 v25, v25, v0
	ds_bpermute_b32 v48, v168, v25
	v_pk_mul_f32 v[0:1], v[70:71], v[50:51]
	v_pk_mul_f32 v[2:3], v[72:73], v[4:5]
	v_pk_mul_f32 v[4:5], v[64:65], v[6:7]
	v_cvt_pk_bf16_f32 v2, v2, v3
	v_cvt_pk_bf16_f32 v3, v0, v1
	s_waitcnt lgkmcnt(0)
	v_add_f32_e32 v0, v25, v48
	ds_bpermute_b32 v1, v169, v0
	v_lshl_add_u64 v[6:7], s[86:87], 0, v[106:107]
	v_cvt_pk_bf16_f32 v4, v4, v5
	v_cvt_pk_bf16_f32 v5, v44, v45
	global_store_dwordx4 v[6:7], v[2:5], off
	s_and_saveexec_b64 s[24:25], s[0:1]
	s_cbranch_execz .LBB0_1065
	v_add_u32_e32 v136, 0x90, v24
	v_lshl_add_u64 v[2:3], v[136:137], 2, s[14:15]
	s_waitcnt lgkmcnt(0)
	v_add_f32_e32 v0, v0, v1
	global_atomic_add_f32 v[2:3], v0, off
;     __device__ __forceinline__ void operator()(const f32x4 (&acc)[2][2][4][2], const Unit& u, int wr, int wc, int fr, int fq) const {
;     ...
;         for (int rg = 0; rg < 8 / RGB; ++rg) {
;             u32x4 braw[INPLACE ? RGB : 1][2]; f32x4 bb[INPLACE ? 1 : RGB][2][2];
; #pragma unroll
;             for (int mm = 0; mm < RGB; ++mm) { const int q = rg * RGB + mm, ai = q >> 2, m = q & 3;
; #pragma unroll
;                 for (int bj = 0; bj < 2; ++bj) { const unsigned e = e0 + (unsigned)((ai * 128 + m * 16) * D + bj * 128);
;                     if constexpr (INPLACE) braw[mm][bj] = *(const u32x4*)(Hc + (size_t)(e * 2u));
;                     else { bb[mm][bj][0] = *(const f32x4*)(bsc + (size_t)(e * 4u)); bb[mm][bj][1] = *(const f32x4*)(bsc + (size_t)(e * 4u + 16u)); } } }
; #pragma unroll
;             for (int mm = 0; mm < RGB; ++mm) { const int q = rg * RGB + mm, ai = q >> 2, m = q & 3; float ssum = 0.f;
; #pragma unroll
;                 for (int bj = 0; bj < 2; ++bj) { const unsigned e = e0 + (unsigned)((ai * 128 + m * 16) * D + bj * 128);
;                     f32x4 r0, r1;
;                     if constexpr (INPLACE) { const u32x4 q4 = braw[mm][bj];
;                         r0 = (f32x4){__uint_as_float(q4[0] << 16), __uint_as_float(q4[0] & 0xffff0000u), __uint_as_float(q4[1] << 16), __uint_as_float(q4[1] & 0xffff0000u)};
;                         r1 = (f32x4){__uint_as_float(q4[2] << 16), __uint_as_float(q4[2] & 0xffff0000u), __uint_as_float(q4[3] << 16), __uint_as_float(q4[3] & 0xffff0000u)}; }
;                     else { r0 = bb[mm][bj][0]; r1 = bb[mm][bj][1]; }
;                     const f32x4 h0 = r0 + gv[bj][0] * (acc[ai][bj][m][0] + bv[bj][0]), h1 = r1 + gv[bj][1] * (acc[ai][bj][m][1] + bv[bj][1]);
;                     { u32x4 w; w.x = cvt_pk_bf16(h0[0], h0[1]); w.y = cvt_pk_bf16(h0[2], h0[3]); w.z = cvt_pk_bf16(h1[0], h1[1]); w.w = cvt_pk_bf16(h1[2], h1[3]); ST16(1, Hc + (size_t)(e * 2u), w); }
;                     if (FUSE) { ssum += ((h0[0] * h0[0] + h0[1] * h0[1]) + (h0[2] * h0[2] + h0[3] * h0[3])) + ((h1[0] * h1[0] + h1[1] * h1[1]) + (h1[2] * h1[2] + h1[3] * h1[3]));
;                         const f32x4 z0 = h0 * wv[bj][0], z1 = h1 * wv[bj][1];
;                         u32x4 w; w.x = cvt_pk_bf16(z0[0], z0[1]); w.y = cvt_pk_bf16(z0[2], z0[3]); w.z = cvt_pk_bf16(z1[0], z1[1]); w.w = cvt_pk_bf16(z1[2], z1[3]);
.LBB0_1065:
	s_or_b64 exec, exec, s[24:25]
	v_add_u32_e32 v25, 0x50000, v196
	v_add_u32_e32 v45, 0x50100, v196
	v_add_u32_e32 v136, 0x58000, v196
	v_add_u32_e32 v44, 0x58100, v196
	s_waitcnt lgkmcnt(0)
	s_waitcnt vmcnt(8)
	v_mov_b64_e32 v[46:47], v[238:239]
	v_mov_b64_e32 v[48:49], v[240:241]
	v_mov_b64_e32 v[50:51], v[242:243]
	v_mov_b64_e32 v[52:53], v[244:245]
	v_mov_b64_e32 v[4:5], v[246:247]
	v_mov_b64_e32 v[6:7], v[248:249]
	v_mov_b64_e32 v[0:1], v[250:251]
	v_mov_b64_e32 v[2:3], v[254:255]
	s_nop 0
	v_lshlrev_b32_e32 v54, 16, v46
	v_and_b32_e32 v55, 0xffff0000, v46
	v_lshlrev_b32_e32 v46, 16, v47
	v_and_b32_e32 v47, 0xffff0000, v47
	v_lshlrev_b32_e32 v56, 16, v48
	v_and_b32_e32 v57, 0xffff0000, v48
	v_lshlrev_b32_e32 v48, 16, v49
	v_and_b32_e32 v49, 0xffff0000, v49
	s_nop 0
	v_lshlrev_b32_e32 v58, 16, v50
	v_and_b32_e32 v59, 0xffff0000, v50
	v_lshlrev_b32_e32 v50, 16, v51
	v_and_b32_e32 v51, 0xffff0000, v51
	v_lshlrev_b32_e32 v74, 16, v52
	v_and_b32_e32 v75, 0xffff0000, v52
	v_lshlrev_b32_e32 v52, 16, v53
	v_and_b32_e32 v53, 0xffff0000, v53
	v_pk_fma_f32 v[46:47], v[28:29], v[94:95], v[46:47]
	v_pk_fma_f32 v[54:55], v[30:31], v[86:87], v[54:55]
	v_pk_fma_f32 v[34:35], v[34:35], v[84:85], v[48:49]
	v_pk_fma_f32 v[32:33], v[32:33], v[82:83], v[56:57]
	v_pk_fma_f32 v[42:43], v[42:43], v[68:69], v[50:51]
	v_pk_fma_f32 v[40:41], v[40:41], v[66:67], v[58:59]
	v_pk_fma_f32 v[38:39], v[38:39], v[60:61], v[52:53]
	v_pk_fma_f32 v[36:37], v[36:37], v[26:27], v[74:75]
	v_cvt_pk_bf16_f32 v28, v54, v55
	v_cvt_pk_bf16_f32 v29, v46, v47
	v_cvt_pk_bf16_f32 v30, v32, v33
	v_cvt_pk_bf16_f32 v31, v34, v35
	v_mul_f32_e32 v58, v55, v55
	v_mul_f32_e32 v59, v47, v47
	v_mul_f32_e32 v74, v33, v33
	v_mul_f32_e32 v75, v35, v35
	v_pk_mul_f32 v[48:49], v[102:103], v[46:47]
	v_pk_mul_f32 v[50:51], v[104:105], v[54:55]
	v_pk_mul_f32 v[52:53], v[98:99], v[34:35]
	v_pk_mul_f32 v[56:57], v[100:101], v[32:33]
	v_mul_f32_e32 v33, v41, v41
	v_mul_f32_e32 v35, v43, v43
	v_mul_f32_e32 v47, v37, v37
	v_mul_f32_e32 v55, v39, v39
	v_fmac_f32_e32 v58, v54, v54
	v_fmac_f32_e32 v59, v46, v46
	v_fmac_f32_e32 v74, v32, v32
	v_fmac_f32_e32 v75, v34, v34
	v_fmac_f32_e32 v33, v40, v40
	v_fmac_f32_e32 v35, v42, v42
	v_fmac_f32_e32 v47, v36, v36
	v_fmac_f32_e32 v55, v38, v38
	global_store_dwordx4 v25, v[28:31], s[16:17]
	v_add_f32_e32 v32, v58, v59
	v_add_f32_e32 v34, v74, v75
	v_cvt_pk_bf16_f32 v28, v50, v51
	v_cvt_pk_bf16_f32 v29, v48, v49
	v_cvt_pk_bf16_f32 v30, v56, v57
	v_cvt_pk_bf16_f32 v31, v52, v53
	global_store_dwordx4 v25, v[28:31], s[86:87]
	v_add_f32_e32 v25, v33, v35
	v_add_f32_e32 v33, v47, v55
	v_add_f32_e32 v32, v32, v34
	v_add_f32_e32 v25, v25, v33
	v_cvt_pk_bf16_f32 v28, v40, v41
	v_cvt_pk_bf16_f32 v29, v42, v43
	v_cvt_pk_bf16_f32 v30, v36, v37
	v_cvt_pk_bf16_f32 v31, v38, v39
	v_add_f32_e32 v25, v32, v25
	global_store_dwordx4 v45, v[28:31], s[16:17]
	ds_bpermute_b32 v31, v168, v25
	v_pk_mul_f32 v[32:33], v[70:71], v[42:43]
	v_pk_mul_f32 v[28:29], v[72:73], v[40:41]
	v_pk_mul_f32 v[34:35], v[62:63], v[38:39]
	v_cvt_pk_bf16_f32 v30, v28, v29
	s_waitcnt lgkmcnt(0)
	v_add_f32_e32 v25, v25, v31
	ds_bpermute_b32 v28, v169, v25
	v_pk_mul_f32 v[36:37], v[64:65], v[36:37]
	v_cvt_pk_bf16_f32 v31, v32, v33
	s_nop 0
	v_cvt_pk_bf16_f32 v32, v36, v37
	v_cvt_pk_bf16_f32 v33, v34, v35
	global_store_dwordx4 v45, v[30:33], s[86:87]
	s_and_saveexec_b64 s[24:25], s[0:1]
	s_cbranch_execz .LBB0_1067
	v_add_u32_e32 v30, 0xa0, v24
	v_mov_b32_e32 v31, v137
	v_lshl_add_u64 v[30:31], v[30:31], 2, s[14:15]
	s_waitcnt lgkmcnt(0)
	v_add_f32_e32 v25, v25, v28
	global_atomic_add_f32 v[30:31], v25, off
.LBB0_1067:
	s_or_b64 exec, exec, s[24:25]
	s_nop 0
	v_lshlrev_b32_e32 v32, 16, v4
	v_and_b32_e32 v33, 0xffff0000, v4
	v_lshlrev_b32_e32 v4, 16, v5
	v_and_b32_e32 v5, 0xffff0000, v5
	s_waitcnt lgkmcnt(0)
	v_lshl_add_u64 v[28:29], s[16:17], 0, v[136:137]
	v_lshlrev_b32_e32 v34, 16, v6
	v_and_b32_e32 v35, 0xffff0000, v6
	v_lshlrev_b32_e32 v6, 16, v7
	v_and_b32_e32 v7, 0xffff0000, v7
	v_pk_fma_f32 v[22:23], v[22:23], v[94:95], v[4:5]
	v_pk_fma_f32 v[20:21], v[20:21], v[86:87], v[32:33]
	v_pk_fma_f32 v[18:19], v[18:19], v[84:85], v[6:7]
	v_cvt_pk_bf16_f32 v4, v20, v21
	v_cvt_pk_bf16_f32 v5, v22, v23
	v_pk_fma_f32 v[16:17], v[16:17], v[82:83], v[34:35]
	v_mov_b32_e32 v45, v137
	v_cvt_pk_bf16_f32 v6, v16, v17
	v_cvt_pk_bf16_f32 v7, v18, v19
	global_store_dwordx4 v[28:29], v[4:7], off
	v_lshl_add_u64 v[30:31], s[16:17], 0, v[44:45]
	s_nop 0
	v_mul_f32_e32 v4, v21, v21
	v_mul_f32_e32 v5, v23, v23
	v_fmac_f32_e32 v4, v20, v20
	v_fmac_f32_e32 v5, v22, v22
	v_add_f32_e32 v4, v4, v5
	v_mul_f32_e32 v5, v17, v17
	v_mul_f32_e32 v6, v19, v19
	v_fmac_f32_e32 v5, v16, v16
	v_fmac_f32_e32 v6, v18, v18
	v_add_f32_e32 v5, v5, v6
	v_add_f32_e32 v25, v4, v5
	v_pk_mul_f32 v[6:7], v[102:103], v[22:23]
	v_pk_mul_f32 v[4:5], v[104:105], v[20:21]
	v_pk_mul_f32 v[16:17], v[100:101], v[16:17]
	v_cvt_pk_bf16_f32 v4, v4, v5
	v_cvt_pk_bf16_f32 v5, v6, v7
	v_pk_mul_f32 v[18:19], v[98:99], v[18:19]
	v_cvt_pk_bf16_f32 v6, v16, v17
	v_lshl_add_u64 v[16:17], s[86:87], 0, v[136:137]
	v_cvt_pk_bf16_f32 v7, v18, v19
	global_store_dwordx4 v[16:17], v[4:7], off
	s_nop 0
	s_nop 0
	v_lshlrev_b32_e32 v4, 16, v0
	v_and_b32_e32 v5, 0xffff0000, v0
	v_lshlrev_b32_e32 v0, 16, v1
	v_and_b32_e32 v1, 0xffff0000, v1
	v_lshlrev_b32_e32 v6, 16, v2
	v_and_b32_e32 v7, 0xffff0000, v2
	v_lshlrev_b32_e32 v2, 16, v3
	v_and_b32_e32 v3, 0xffff0000, v3
	v_pk_fma_f32 v[14:15], v[14:15], v[68:69], v[0:1]
	v_pk_fma_f32 v[4:5], v[12:13], v[66:67], v[4:5]
	v_pk_fma_f32 v[10:11], v[10:11], v[60:61], v[2:3]
	v_cvt_pk_bf16_f32 v0, v4, v5
	v_cvt_pk_bf16_f32 v1, v14, v15
	v_pk_fma_f32 v[6:7], v[8:9], v[26:27], v[6:7]
	v_pk_mul_f32 v[8:9], v[62:63], v[10:11]
	v_cvt_pk_bf16_f32 v2, v6, v7
	v_cvt_pk_bf16_f32 v3, v10, v11
	global_store_dwordx4 v[30:31], v[0:3], off
	s_nop 1
	v_mul_f32_e32 v0, v5, v5
	v_mul_f32_e32 v1, v15, v15
	v_fmac_f32_e32 v0, v4, v4
	v_fmac_f32_e32 v1, v14, v14
	v_add_f32_e32 v0, v0, v1
	v_mul_f32_e32 v1, v7, v7
	v_mul_f32_e32 v2, v11, v11
	v_fmac_f32_e32 v1, v6, v6
	v_fmac_f32_e32 v2, v10, v10
	v_add_f32_e32 v1, v1, v2
	v_add_f32_e32 v0, v0, v1
	v_add_f32_e32 v12, v25, v0
	ds_bpermute_b32 v13, v168, v12
	v_pk_mul_f32 v[0:1], v[70:71], v[14:15]
	v_pk_mul_f32 v[2:3], v[72:73], v[4:5]
	v_pk_mul_f32 v[4:5], v[64:65], v[6:7]
	v_cvt_pk_bf16_f32 v2, v2, v3
	v_cvt_pk_bf16_f32 v3, v0, v1
	s_waitcnt lgkmcnt(0)
	v_add_f32_e32 v0, v12, v13
	ds_bpermute_b32 v1, v169, v0
	v_lshl_add_u64 v[6:7], s[86:87], 0, v[44:45]
	v_cvt_pk_bf16_f32 v4, v4, v5
	v_cvt_pk_bf16_f32 v5, v8, v9
	global_store_dwordx4 v[6:7], v[2:5], off
	s_and_saveexec_b64 s[24:25], s[0:1]
	s_cbranch_execz .LBB0_1069
	v_add_u32_e32 v136, 0xb0, v24
	v_lshl_add_u64 v[2:3], v[136:137], 2, s[14:15]
	s_waitcnt lgkmcnt(0)
	v_add_f32_e32 v0, v0, v1
	global_atomic_add_f32 v[2:3], v0, off
